# speedup vs baseline: 1.0878x; 1.0307x over previous
; #define WAIT_V(n) asm volatile("s_waitcnt vmcnt(%0)" ::"n"(n) : "memory")
;     ...
;     f32x4 acc[MT][4];
; #pragma unroll
;     for (int m = 0; m < MT; ++m)
; #pragma unroll
;       for (int n = 0; n < 4; ++n) acc[m][n] = f32x4{0.f, 0.f, 0.f, 0.f};
;     for (int t = 0; t < nt; ++t) {
;       const int cur = t & 1;
;       const char* sa = shm + cur * STAGE_B;
;       const char* sn = shm + (cur ^ 1) * STAGE_B;
;       const bool more = (t + 1 < nt) || (nitem < ntiles);
; #pragma unroll
;       for (int ks = 0; ks < 2; ++ks) {
; #pragma unroll
;         for (int p = 0; p < NP; ++p) {
;           const int q = ks * NP + p;
;           acc[p * 2][0] = __builtin_amdgcn_mfma_f32_16x16x32_bf16(Bq[BDBL ? ks : 0][0], Aq[q & 1][0], acc[p * 2][0], 0, 0, 0);
;           __builtin_amdgcn_sched_barrier(0);
;           if (q == 2 * NP - 1) {
;             WAIT_V(0);
;             __syncthreads();
;             if (more) {
;               if constexpr (BDBL) {
; #pragma unroll
;                 for (int n = 0; n < 4; ++n) Bq[0][n] = *(const bf16x8*)(sn + boff + (n * 2 + 0) * 1024);
;               }
; #pragma unroll
;               for (int i = 0; i < 2; ++i) Aq[0][i] = *(const bf16x8*)(sn + aoff + (i * 2 + 0) * 1024);
;             }
;           } else if (p + 1 < NP) {
; #pragma unroll
;             for (int i = 0; i < 2; ++i) Aq[(q + 1) & 1][i] = *(const bf16x8*)(sa + aoff + (((p + 1) * 2 + i) * 2 + ks) * 1024);
;           } else {
;             if constexpr (BDBL) {
; #pragma unroll
;               for (int n = 0; n < 4; ++n) Bq[1][n] = *(const bf16x8*)(sa + boff + (n * 2 + 1) * 1024);
;             }
; #pragma unroll
;             for (int i = 0; i < 2; ++i) Aq[(q + 1) & 1][i] = *(const bf16x8*)(sa + aoff + (i * 2 + 1) * 1024);
;           }
;           __builtin_amdgcn_sched_barrier(0);
; #pragma unroll
;           for (int i = 0; i < 2; ++i)
; #pragma unroll
;             for (int n = 0; n < 4; ++n)
;               if (i + n > 0)
;                 acc[p * 2 + i][n] = __builtin_amdgcn_mfma_f32_16x16x32_bf16(Bq[BDBL ? ks : 0][n], Aq[q & 1][i], acc[p * 2 + i][n], 0, 0, 0);
;           __builtin_amdgcn_sched_barrier(0);
;           if (q == GLDS_AT) {
;             if (t + 1 < nt) GLDS_STAGE(cur ^ 1, t + 1, Ab, Bb);
;             else if (nitem < ntiles) GLDS_STAGE(0, 0, nAb, nBb);
;             __builtin_amdgcn_sched_barrier(0);
;           }
.LBB0_185:
	v_lshl_add_u64 v[152:153], s[16:17], 0, v[218:219]
	v_lshl_add_u64 v[154:155], s[0:1], 0, v[218:219]
	s_mov_b64 s[0:1], 0
	s_waitcnt lgkmcnt(0)
	s_nop 0
	v_mfma_f32_16x16x32_bf16 v[148:151], v[12:15], v[20:23], 0
	s_and_b32 s16, s51, 0x10000
	s_xor_b32 s17, s16, 0x10000
	v_add_u32_e32 v184, s16, v220
	v_or_b32_e32 v176, s16, v221
	v_bitop3_b32 v185, s51, v221, v233 bitop3:0xce
	v_add_u32_e32 v186, s17, v220
	ds_read_b128 v[156:159], v184 offset:4096
	ds_read_b128 v[160:163], v184 offset:6144
	v_mfma_f32_16x16x32_bf16 v[144:147], v[8:11], v[20:23], 0
	s_add_i32 s16, s17, s19
	v_lshl_add_u64 v[180:181], v[152:153], 0, s[0:1]
	v_mfma_f32_16x16x32_bf16 v[140:143], v[4:7], v[20:23], 0
	v_lshl_add_u64 v[182:183], v[180:181], 0, s[38:39]
	s_mov_b32 m0, s16
	v_mfma_f32_16x16x32_bf16 v[20:23], v[0:3], v[20:23], 0
	s_add_i32 s17, s16, 0x8000
	global_load_lds_dwordx4 v[182:183], off
	v_mfma_f32_16x16x32_bf16 v[132:135], v[12:15], v[16:19], 0
	v_lshl_add_u64 v[182:183], v[180:181], 0, s[82:83]
	s_add_i32 m0, s16, 0x2000
	v_mfma_f32_16x16x32_bf16 v[128:131], v[8:11], v[16:19], 0
	global_load_lds_dwordx4 v[182:183], off
	v_lshl_add_u64 v[182:183], v[180:181], 0, s[78:79]
	v_mfma_f32_16x16x32_bf16 v[124:127], v[4:7], v[16:19], 0
	s_add_i32 m0, s16, 0x4000
	v_lshl_add_u64 v[180:181], v[180:181], 0, s[2:3]
	v_mfma_f32_16x16x32_bf16 v[16:19], v[0:3], v[16:19], 0
	global_load_lds_dwordx4 v[182:183], off
	s_add_i32 m0, s16, 0x6000
	s_waitcnt lgkmcnt(1)
	v_mfma_f32_16x16x32_bf16 v[116:119], v[12:15], v[156:159], 0
	s_nop 0
	ds_read_b128 v[120:123], v184 offset:8192
	ds_read_b128 v[136:139], v184 offset:10240
	global_load_lds_dwordx4 v[180:181], off
	v_lshl_add_u64 v[180:181], v[154:155], 0, s[0:1]
	v_mfma_f32_16x16x32_bf16 v[112:115], v[8:11], v[156:159], 0
	v_lshl_add_u64 v[182:183], v[180:181], 0, s[38:39]
	s_mov_b32 m0, s17
	v_mfma_f32_16x16x32_bf16 v[108:111], v[4:7], v[156:159], 0
	global_load_lds_dwordx4 v[182:183], off
	v_lshl_add_u64 v[182:183], v[180:181], 0, s[82:83]
	v_mfma_f32_16x16x32_bf16 v[104:107], v[0:3], v[156:159], 0
	s_add_i32 m0, s16, 0xa000
	s_waitcnt lgkmcnt(2)
	v_mfma_f32_16x16x32_bf16 v[100:103], v[12:15], v[160:163], 0
	global_load_lds_dwordx4 v[182:183], off
	v_lshl_add_u64 v[182:183], v[180:181], 0, s[78:79]
	v_mfma_f32_16x16x32_bf16 v[96:99], v[8:11], v[160:163], 0
	s_add_i32 m0, s16, 0xc000
	v_lshl_add_u64 v[180:181], v[180:181], 0, s[2:3]
	v_mfma_f32_16x16x32_bf16 v[92:95], v[4:7], v[160:163], 0
	global_load_lds_dwordx4 v[182:183], off
	s_add_i32 m0, s16, 0xe000
	v_mfma_f32_16x16x32_bf16 v[88:91], v[0:3], v[160:163], 0
	global_load_lds_dwordx4 v[180:181], off
	s_waitcnt lgkmcnt(1)
	v_mfma_f32_16x16x32_bf16 v[84:87], v[12:15], v[120:123], 0
	ds_read_b128 v[156:159], v184 offset:12288
	ds_read_b128 v[160:163], v184 offset:14336
	v_mfma_f32_16x16x32_bf16 v[80:83], v[8:11], v[120:123], 0
	v_mfma_f32_16x16x32_bf16 v[76:79], v[4:7], v[120:123], 0
	v_mfma_f32_16x16x32_bf16 v[72:75], v[0:3], v[120:123], 0
	s_waitcnt lgkmcnt(2)
	v_mfma_f32_16x16x32_bf16 v[68:71], v[12:15], v[136:139], 0
	v_mfma_f32_16x16x32_bf16 v[64:67], v[8:11], v[136:139], 0
	v_mfma_f32_16x16x32_bf16 v[60:63], v[4:7], v[136:139], 0
	v_mfma_f32_16x16x32_bf16 v[56:59], v[0:3], v[136:139], 0
	s_waitcnt lgkmcnt(1)
	v_mfma_f32_16x16x32_bf16 v[52:55], v[12:15], v[156:159], 0
	ds_read_b128 v[164:167], v176 offset:33792
	ds_read_b128 v[168:171], v176 offset:35840
	ds_read_b128 v[172:175], v176 offset:37888
	ds_read_b128 v[176:179], v176 offset:39936
	ds_read_b128 v[120:123], v184 offset:1024
	ds_read_b128 v[180:183], v184 offset:3072
	v_mfma_f32_16x16x32_bf16 v[48:51], v[8:11], v[156:159], 0
	v_mfma_f32_16x16x32_bf16 v[44:47], v[4:7], v[156:159], 0
	v_mfma_f32_16x16x32_bf16 v[40:43], v[0:3], v[156:159], 0
	s_waitcnt lgkmcnt(6)
	v_mfma_f32_16x16x32_bf16 v[36:39], v[12:15], v[160:163], 0
	v_mfma_f32_16x16x32_bf16 v[32:35], v[8:11], v[160:163], 0
	v_mfma_f32_16x16x32_bf16 v[28:31], v[4:7], v[160:163], 0
	v_mfma_f32_16x16x32_bf16 v[24:27], v[0:3], v[160:163], 0
	s_waitcnt lgkmcnt(0)
	v_mfma_f32_16x16x32_bf16 v[148:151], v[164:167], v[120:123], v[148:151]
	ds_read_b128 v[0:3], v184 offset:5120
	ds_read_b128 v[4:7], v184 offset:7168
	v_mfma_f32_16x16x32_bf16 v[144:147], v[168:171], v[120:123], v[144:147]
	v_mfma_f32_16x16x32_bf16 v[140:143], v[172:175], v[120:123], v[140:143]
	v_mfma_f32_16x16x32_bf16 v[136:139], v[176:179], v[120:123], v[20:23]
	v_mfma_f32_16x16x32_bf16 v[132:135], v[164:167], v[180:183], v[132:135]
	v_mfma_f32_16x16x32_bf16 v[128:131], v[168:171], v[180:183], v[128:131]
	v_mfma_f32_16x16x32_bf16 v[124:127], v[172:175], v[180:183], v[124:127]
	v_mfma_f32_16x16x32_bf16 v[120:123], v[176:179], v[180:183], v[16:19]
	s_waitcnt lgkmcnt(1)
	v_mfma_f32_16x16x32_bf16 v[116:119], v[164:167], v[0:3], v[116:119]
	ds_read_b128 v[8:11], v184 offset:9216
	ds_read_b128 v[12:15], v184 offset:11264
	v_mfma_f32_16x16x32_bf16 v[112:115], v[168:171], v[0:3], v[112:115]
	v_mfma_f32_16x16x32_bf16 v[108:111], v[172:175], v[0:3], v[108:111]
	v_mfma_f32_16x16x32_bf16 v[104:107], v[176:179], v[0:3], v[104:107]
	s_waitcnt lgkmcnt(2)
	v_mfma_f32_16x16x32_bf16 v[100:103], v[164:167], v[4:7], v[100:103]
	v_mfma_f32_16x16x32_bf16 v[96:99], v[168:171], v[4:7], v[96:99]
	v_mfma_f32_16x16x32_bf16 v[92:95], v[172:175], v[4:7], v[92:95]
	v_mfma_f32_16x16x32_bf16 v[88:91], v[176:179], v[4:7], v[88:91]
	s_waitcnt lgkmcnt(1)
	v_mfma_f32_16x16x32_bf16 v[84:87], v[164:167], v[8:11], v[84:87]
	ds_read_b128 v[156:159], v184 offset:13312
	ds_read_b128 v[160:163], v184 offset:15360
	v_mfma_f32_16x16x32_bf16 v[80:83], v[168:171], v[8:11], v[80:83]
	v_mfma_f32_16x16x32_bf16 v[76:79], v[172:175], v[8:11], v[76:79]
	v_mfma_f32_16x16x32_bf16 v[72:75], v[176:179], v[8:11], v[72:75]
	s_waitcnt lgkmcnt(2)
	v_mfma_f32_16x16x32_bf16 v[68:71], v[164:167], v[12:15], v[68:71]
	v_mfma_f32_16x16x32_bf16 v[64:67], v[168:171], v[12:15], v[64:67]
	v_mfma_f32_16x16x32_bf16 v[60:63], v[172:175], v[12:15], v[60:63]
	v_mfma_f32_16x16x32_bf16 v[56:59], v[176:179], v[12:15], v[56:59]
	s_waitcnt lgkmcnt(1)
	v_mfma_f32_16x16x32_bf16 v[52:55], v[164:167], v[156:159], v[52:55]
	s_waitcnt vmcnt(0)
	s_waitcnt lgkmcnt(0)
	s_barrier
	ds_read_b128 v[12:15], v185 offset:32768
	ds_read_b128 v[8:11], v185 offset:34816
	ds_read_b128 v[4:7], v185 offset:36864
	ds_read_b128 v[0:3], v185 offset:38912
	ds_read_b128 v[20:23], v186
	ds_read_b128 v[16:19], v186 offset:2048
	v_mfma_f32_16x16x32_bf16 v[48:51], v[168:171], v[156:159], v[48:51]
	v_mfma_f32_16x16x32_bf16 v[44:47], v[172:175], v[156:159], v[44:47]
	v_mfma_f32_16x16x32_bf16 v[40:43], v[176:179], v[156:159], v[40:43]
	v_mfma_f32_16x16x32_bf16 v[36:39], v[164:167], v[160:163], v[36:39]
	v_mfma_f32_16x16x32_bf16 v[32:35], v[168:171], v[160:163], v[32:35]
	v_mfma_f32_16x16x32_bf16 v[28:31], v[172:175], v[160:163], v[28:31]
	v_mfma_f32_16x16x32_bf16 v[24:27], v[176:179], v[160:163], v[24:27]
	s_add_u32 s0, s0, 0x80
	s_addc_u32 s1, s1, 0
	s_add_i32 s51, s51, 0x10000

; #define WAIT_V(n) asm volatile("s_waitcnt vmcnt(%0)" ::"n"(n) : "memory")
;     ...
;     f32x4 acc[MT][4];
; #pragma unroll
;     for (int m = 0; m < MT; ++m)
; #pragma unroll
;       for (int n = 0; n < 4; ++n) acc[m][n] = f32x4{0.f, 0.f, 0.f, 0.f};
;     for (int t = 0; t < nt; ++t) {
;       const int cur = t & 1;
;       const char* sa = shm + cur * STAGE_B;
;       const char* sn = shm + (cur ^ 1) * STAGE_B;
;       const bool more = (t + 1 < nt) || (nitem < ntiles);
; #pragma unroll
;       for (int ks = 0; ks < 2; ++ks) {
; #pragma unroll
;         for (int p = 0; p < NP; ++p) {
;           const int q = ks * NP + p;
;           acc[p * 2][0] = __builtin_amdgcn_mfma_f32_16x16x32_bf16(Bq[BDBL ? ks : 0][0], Aq[q & 1][0], acc[p * 2][0], 0, 0, 0);
;           __builtin_amdgcn_sched_barrier(0);
;           if (q == 2 * NP - 1) {
;             WAIT_V(0);
;             __syncthreads();
;             if (more) {
;               if constexpr (BDBL) {
; #pragma unroll
;                 for (int n = 0; n < 4; ++n) Bq[0][n] = *(const bf16x8*)(sn + boff + (n * 2 + 0) * 1024);
;               }
; #pragma unroll
;               for (int i = 0; i < 2; ++i) Aq[0][i] = *(const bf16x8*)(sn + aoff + (i * 2 + 0) * 1024);
;             }
;           } else if (p + 1 < NP) {
; #pragma unroll
;             for (int i = 0; i < 2; ++i) Aq[(q + 1) & 1][i] = *(const bf16x8*)(sa + aoff + (((p + 1) * 2 + i) * 2 + ks) * 1024);
;           } else {
;             if constexpr (BDBL) {
; #pragma unroll
;               for (int n = 0; n < 4; ++n) Bq[1][n] = *(const bf16x8*)(sa + boff + (n * 2 + 1) * 1024);
;             }
; #pragma unroll
;             for (int i = 0; i < 2; ++i) Aq[(q + 1) & 1][i] = *(const bf16x8*)(sa + aoff + (i * 2 + 1) * 1024);
;           }
;           __builtin_amdgcn_sched_barrier(0);
; #pragma unroll
;           for (int i = 0; i < 2; ++i)
; #pragma unroll
;             for (int n = 0; n < 4; ++n)
;               if (i + n > 0)
;                 acc[p * 2 + i][n] = __builtin_amdgcn_mfma_f32_16x16x32_bf16(Bq[BDBL ? ks : 0][n], Aq[q & 1][i], acc[p * 2 + i][n], 0, 0, 0);
;           __builtin_amdgcn_sched_barrier(0);
;           if (q == GLDS_AT) {
;             if (t + 1 < nt) GLDS_STAGE(cur ^ 1, t + 1, Ab, Bb);
;             else if (nitem < ntiles) GLDS_STAGE(0, 0, nAb, nBb);
;             __builtin_amdgcn_sched_barrier(0);
;           }
.LBB0_238:
	v_lshl_add_u64 v[152:153], s[18:19], 0, v[226:227]
	v_lshl_add_u64 v[154:155], s[0:1], 0, v[226:227]
	s_mov_b64 s[0:1], 0
	s_waitcnt lgkmcnt(0)
	s_nop 0
	v_mfma_f32_16x16x32_bf16 v[148:151], v[12:15], v[20:23], 0
	s_and_b32 s18, s50, 0x10000
	s_xor_b32 s19, s18, 0x10000
	v_add_u32_e32 v184, s18, v241
	v_or_b32_e32 v176, s18, v242
	v_bitop3_b32 v185, s50, v242, v233 bitop3:0xce
	v_add_u32_e32 v186, s19, v241
	ds_read_b128 v[156:159], v184 offset:4096
	ds_read_b128 v[160:163], v184 offset:6144
	v_mfma_f32_16x16x32_bf16 v[144:147], v[8:11], v[20:23], 0
	s_add_i32 s18, s19, s4
	v_lshl_add_u64 v[180:181], v[152:153], 0, s[0:1]
	v_mfma_f32_16x16x32_bf16 v[140:143], v[4:7], v[20:23], 0
	v_lshl_add_u64 v[182:183], v[180:181], 0, s[38:39]
	s_mov_b32 m0, s18
	v_mfma_f32_16x16x32_bf16 v[20:23], v[0:3], v[20:23], 0
	s_add_i32 s19, s18, 0x8000
	global_load_lds_dwordx4 v[182:183], off
	v_mfma_f32_16x16x32_bf16 v[132:135], v[12:15], v[16:19], 0
	v_lshl_add_u64 v[182:183], v[180:181], 0, s[72:73]
	s_add_i32 m0, s18, 0x2000
	v_mfma_f32_16x16x32_bf16 v[128:131], v[8:11], v[16:19], 0
	global_load_lds_dwordx4 v[182:183], off
	v_lshl_add_u64 v[182:183], v[180:181], 0, s[54:55]
	v_mfma_f32_16x16x32_bf16 v[124:127], v[4:7], v[16:19], 0
	s_add_i32 m0, s18, 0x4000
	v_lshl_add_u64 v[180:181], v[180:181], 0, s[80:81]
	v_mfma_f32_16x16x32_bf16 v[16:19], v[0:3], v[16:19], 0
	global_load_lds_dwordx4 v[182:183], off
	s_add_i32 m0, s18, 0x6000
	s_waitcnt lgkmcnt(1)
	v_mfma_f32_16x16x32_bf16 v[116:119], v[12:15], v[156:159], 0
	s_nop 0
	ds_read_b128 v[120:123], v184 offset:8192
	ds_read_b128 v[136:139], v184 offset:10240
	global_load_lds_dwordx4 v[180:181], off
	v_lshl_add_u64 v[180:181], v[154:155], 0, s[0:1]
	v_mfma_f32_16x16x32_bf16 v[112:115], v[8:11], v[156:159], 0
	v_lshl_add_u64 v[182:183], v[180:181], 0, s[38:39]
	s_mov_b32 m0, s19
	v_mfma_f32_16x16x32_bf16 v[108:111], v[4:7], v[156:159], 0
	global_load_lds_dwordx4 v[182:183], off
	v_lshl_add_u64 v[182:183], v[180:181], 0, s[72:73]
	v_mfma_f32_16x16x32_bf16 v[104:107], v[0:3], v[156:159], 0
	s_add_i32 m0, s18, 0xa000
	s_waitcnt lgkmcnt(2)
	v_mfma_f32_16x16x32_bf16 v[100:103], v[12:15], v[160:163], 0
	global_load_lds_dwordx4 v[182:183], off
	v_lshl_add_u64 v[182:183], v[180:181], 0, s[54:55]
	v_mfma_f32_16x16x32_bf16 v[96:99], v[8:11], v[160:163], 0
	s_add_i32 m0, s18, 0xc000
	v_lshl_add_u64 v[180:181], v[180:181], 0, s[80:81]
	v_mfma_f32_16x16x32_bf16 v[92:95], v[4:7], v[160:163], 0
	global_load_lds_dwordx4 v[182:183], off
	s_add_i32 m0, s18, 0xe000
	v_mfma_f32_16x16x32_bf16 v[88:91], v[0:3], v[160:163], 0
	global_load_lds_dwordx4 v[180:181], off
	s_waitcnt lgkmcnt(1)
	v_mfma_f32_16x16x32_bf16 v[84:87], v[12:15], v[120:123], 0
	ds_read_b128 v[156:159], v184 offset:12288
	ds_read_b128 v[160:163], v184 offset:14336
	v_mfma_f32_16x16x32_bf16 v[80:83], v[8:11], v[120:123], 0
	v_mfma_f32_16x16x32_bf16 v[76:79], v[4:7], v[120:123], 0
	v_mfma_f32_16x16x32_bf16 v[72:75], v[0:3], v[120:123], 0
	s_waitcnt lgkmcnt(2)
	v_mfma_f32_16x16x32_bf16 v[68:71], v[12:15], v[136:139], 0
	v_mfma_f32_16x16x32_bf16 v[64:67], v[8:11], v[136:139], 0
	v_mfma_f32_16x16x32_bf16 v[60:63], v[4:7], v[136:139], 0
	v_mfma_f32_16x16x32_bf16 v[56:59], v[0:3], v[136:139], 0
	s_waitcnt lgkmcnt(1)
	v_mfma_f32_16x16x32_bf16 v[52:55], v[12:15], v[156:159], 0
	ds_read_b128 v[164:167], v176 offset:33792
	ds_read_b128 v[168:171], v176 offset:35840
	ds_read_b128 v[172:175], v176 offset:37888
	ds_read_b128 v[176:179], v176 offset:39936
	ds_read_b128 v[120:123], v184 offset:1024
	ds_read_b128 v[180:183], v184 offset:3072
	v_mfma_f32_16x16x32_bf16 v[48:51], v[8:11], v[156:159], 0
	v_mfma_f32_16x16x32_bf16 v[44:47], v[4:7], v[156:159], 0
	v_mfma_f32_16x16x32_bf16 v[40:43], v[0:3], v[156:159], 0
	s_waitcnt lgkmcnt(6)
	v_mfma_f32_16x16x32_bf16 v[36:39], v[12:15], v[160:163], 0
	v_mfma_f32_16x16x32_bf16 v[32:35], v[8:11], v[160:163], 0
	v_mfma_f32_16x16x32_bf16 v[28:31], v[4:7], v[160:163], 0
	v_mfma_f32_16x16x32_bf16 v[24:27], v[0:3], v[160:163], 0
	s_waitcnt lgkmcnt(0)
	v_mfma_f32_16x16x32_bf16 v[148:151], v[164:167], v[120:123], v[148:151]
	ds_read_b128 v[0:3], v184 offset:5120
	ds_read_b128 v[4:7], v184 offset:7168
	v_mfma_f32_16x16x32_bf16 v[144:147], v[168:171], v[120:123], v[144:147]
	v_mfma_f32_16x16x32_bf16 v[140:143], v[172:175], v[120:123], v[140:143]
	v_mfma_f32_16x16x32_bf16 v[136:139], v[176:179], v[120:123], v[20:23]
	v_mfma_f32_16x16x32_bf16 v[132:135], v[164:167], v[180:183], v[132:135]
	v_mfma_f32_16x16x32_bf16 v[128:131], v[168:171], v[180:183], v[128:131]
	v_mfma_f32_16x16x32_bf16 v[124:127], v[172:175], v[180:183], v[124:127]
	v_mfma_f32_16x16x32_bf16 v[120:123], v[176:179], v[180:183], v[16:19]
	s_waitcnt lgkmcnt(1)
	v_mfma_f32_16x16x32_bf16 v[116:119], v[164:167], v[0:3], v[116:119]
	ds_read_b128 v[8:11], v184 offset:9216
	ds_read_b128 v[12:15], v184 offset:11264
	v_mfma_f32_16x16x32_bf16 v[112:115], v[168:171], v[0:3], v[112:115]
	v_mfma_f32_16x16x32_bf16 v[108:111], v[172:175], v[0:3], v[108:111]
	v_mfma_f32_16x16x32_bf16 v[104:107], v[176:179], v[0:3], v[104:107]
	s_waitcnt lgkmcnt(2)
	v_mfma_f32_16x16x32_bf16 v[100:103], v[164:167], v[4:7], v[100:103]
	v_mfma_f32_16x16x32_bf16 v[96:99], v[168:171], v[4:7], v[96:99]
	v_mfma_f32_16x16x32_bf16 v[92:95], v[172:175], v[4:7], v[92:95]
	v_mfma_f32_16x16x32_bf16 v[88:91], v[176:179], v[4:7], v[88:91]
	s_waitcnt lgkmcnt(1)
	v_mfma_f32_16x16x32_bf16 v[84:87], v[164:167], v[8:11], v[84:87]
	ds_read_b128 v[156:159], v184 offset:13312
	ds_read_b128 v[160:163], v184 offset:15360
	v_mfma_f32_16x16x32_bf16 v[80:83], v[168:171], v[8:11], v[80:83]
	v_mfma_f32_16x16x32_bf16 v[76:79], v[172:175], v[8:11], v[76:79]
	v_mfma_f32_16x16x32_bf16 v[72:75], v[176:179], v[8:11], v[72:75]
	s_waitcnt lgkmcnt(2)
	v_mfma_f32_16x16x32_bf16 v[68:71], v[164:167], v[12:15], v[68:71]
	v_mfma_f32_16x16x32_bf16 v[64:67], v[168:171], v[12:15], v[64:67]
	v_mfma_f32_16x16x32_bf16 v[60:63], v[172:175], v[12:15], v[60:63]
	v_mfma_f32_16x16x32_bf16 v[56:59], v[176:179], v[12:15], v[56:59]
	s_waitcnt lgkmcnt(1)
	v_mfma_f32_16x16x32_bf16 v[52:55], v[164:167], v[156:159], v[52:55]
	s_waitcnt vmcnt(0)
	s_waitcnt lgkmcnt(0)
	s_barrier
	ds_read_b128 v[12:15], v185 offset:32768
	ds_read_b128 v[8:11], v185 offset:34816
	ds_read_b128 v[4:7], v185 offset:36864
	ds_read_b128 v[0:3], v185 offset:38912
	ds_read_b128 v[20:23], v186
	ds_read_b128 v[16:19], v186 offset:2048
	v_mfma_f32_16x16x32_bf16 v[48:51], v[168:171], v[156:159], v[48:51]
	v_mfma_f32_16x16x32_bf16 v[44:47], v[172:175], v[156:159], v[44:47]
	v_mfma_f32_16x16x32_bf16 v[40:43], v[176:179], v[156:159], v[40:43]
	v_mfma_f32_16x16x32_bf16 v[36:39], v[164:167], v[160:163], v[36:39]
	v_mfma_f32_16x16x32_bf16 v[32:35], v[168:171], v[160:163], v[32:35]
	v_mfma_f32_16x16x32_bf16 v[28:31], v[172:175], v[160:163], v[28:31]
	v_mfma_f32_16x16x32_bf16 v[24:27], v[176:179], v[160:163], v[24:27]
	s_add_u32 s0, s0, 0x80
	s_addc_u32 s1, s1, 0
	s_add_i32 s50, s50, 0x10000

; __device__ __forceinline__ int otid() { int t = threadIdx.x; asm volatile("" : "+v"(t)); return t; }
; __device__ __forceinline__ void ln_phase(float* X, u16* H, const float* g, const float* b, const float* shift,
;                                          const float* scale, int M, float* outp, const float* part = nullptr) {
;   const int tid_ = otid(); const int wid = tid_ >> 6, lane = tid_ & 63;
;   float4 nx[4];
;   {
;     const int r0 = blockIdx.x * 8 + wid;
;     if (r0 < M) {
; #pragma unroll
;       for (int i = 0; i < 4; ++i) nx[i] = *(const float4*)(X + (size_t)r0 * DM + i * 256 + lane * 4);
;     }
;   }
;   for (int row = blockIdx.x * 8 + wid; row < M; row += GRID * 8) {
;     float4 v[4];
;     float* xr = X + (size_t)row * DM;
; #pragma unroll
;     for (int i = 0; i < 4; ++i) v[i] = nx[i];
;     {
;       const int nrow = row + GRID * 8;
;       if (nrow < M) {
; #pragma unroll
;         for (int i = 0; i < 4; ++i) nx[i] = *(const float4*)(X + (size_t)nrow * DM + i * 256 + lane * 4);
;       }
;     }
;     if (part != nullptr && row >= MLAT) {
; #pragma unroll
;       for (int i = 0; i < 4; ++i) {
;         const float4 p4 = *(const float4*)(part + (size_t)(row - MLAT) * DM + i * 256 + lane * 4);
;         v[i].x += p4.x; v[i].y += p4.y; v[i].z += p4.z; v[i].w += p4.w;
;       }
;     }
;     float s = 0.f;
; #pragma unroll
;     for (int i = 0; i < 4; ++i) s += v[i].x + v[i].y + v[i].z + v[i].w;
;     const float mu = wave_sum(s) * (1.0f / 1024.0f);
;     float q = 0.f;
; #pragma unroll
;     for (int i = 0; i < 4; ++i) {
;       v[i].x -= mu; v[i].y -= mu; v[i].z -= mu; v[i].w -= mu;
;       q += v[i].x * v[i].x + v[i].y * v[i].y + v[i].z * v[i].z + v[i].w * v[i].w;
;     }
;     const float rstd = rsqrtf(wave_sum(q) * (1.0f / 1024.0f) + EPS);
.LBB0_363:
	s_or_b64 exec, exec, s[0:1]
	s_and_b64 s[0:1], s[26:27], exec
	v_readlane_b32 s1, v255, 49
	s_cselect_b32 s0, 0, 2
	s_mul_i32 s1, s1, 3
	s_add_i32 s0, s0, s1
	s_lshl_b32 s74, s0, 10
	v_readlane_b32 s4, v250, 42
	s_lshl_b64 s[0:1], s[74:75], 2
	v_readlane_b32 s10, v250, 48
	v_readlane_b32 s16, v250, 54
	v_readlane_b32 s11, v250, 49
	v_readlane_b32 s17, v250, 55
	s_add_u32 s10, s16, s0
	v_readlane_b32 s14, v250, 52
	v_readlane_b32 s18, v250, 56
	s_addc_u32 s11, s17, s1
	v_readlane_b32 s5, v250, 43
	v_readlane_b32 s15, v250, 53
	v_readlane_b32 s19, v250, 57
	s_add_u32 s14, s18, s0
	s_addc_u32 s15, s19, s1
	v_readlane_b32 s4, v255, 54
	s_and_b64 s[0:1], s[90:91], exec
	v_readlane_b32 s5, v255, 55
	s_cselect_b32 s17, s93, 0
	s_cselect_b32 s16, s92, 0
	s_mov_b64 s[0:1], -1
	s_and_b64 vcc, exec, s[4:5]
	s_barrier
	v_readlane_b32 s6, v250, 44
	v_readlane_b32 s7, v250, 45
	v_readlane_b32 s8, v250, 46
	v_readlane_b32 s9, v250, 47
	v_readlane_b32 s12, v250, 50
	v_readlane_b32 s13, v250, 51
	s_cbranch_vccz .LBB0_400
	v_readlane_b32 s0, v254, 47
	v_readlane_b32 s1, v254, 48
	s_andn2_b64 vcc, exec, s[0:1]
	s_mov_b64 s[0:1], -1
	s_cbranch_vccnz .LBB0_373
	v_mov_b32_e32 v0, v228
	v_readlane_b32 s0, v254, 38
	v_ashrrev_i32_e32 v1, 6, v0
	v_readlane_b32 s1, v254, 39
	v_add_u32_e32 v48, s0, v1
	v_cmp_gt_i32_e32 vcc, s60, v48
	s_and_saveexec_b64 s[6:7], vcc
	s_cbranch_execz .LBB0_372
	v_ashrrev_i32_e32 v49, 31, v48
	v_lshlrev_b64 v[32:33], 12, v[48:49]
	v_lshlrev_b32_e32 v1, 4, v0
	v_lshl_add_u64 v[2:3], s[36:37], 0, v[32:33]
	v_and_b32_e32 v224, 0x3f0, v1
	v_lshl_add_u64 v[2:3], v[2:3], 0, v[224:225]
	global_load_dwordx4 v[28:31], v[2:3], off
	global_load_dwordx4 v[16:19], v[2:3], off offset:1024
	global_load_dwordx4 v[20:23], v[2:3], off offset:2048
	global_load_dwordx4 v[24:27], v[2:3], off offset:3072
	v_readlane_b32 s0, v254, 50
	v_readlane_b32 s1, v254, 51
	v_and_b32_e32 v0, 63, v0
	v_lshlrev_b64 v[44:45], 11, v[48:49]
	v_lshl_add_u64 v[40:41], s[0:1], 0, v[224:225]
	v_readlane_b32 s0, v254, 52
	v_readlane_b32 s1, v254, 53
	v_lshl_add_u64 v[34:35], s[16:17], 0, v[224:225]
	v_lshl_add_u64 v[36:37], s[10:11], 0, v[224:225]
	v_lshl_add_u64 v[38:39], s[14:15], 0, v[224:225]
	v_lshl_add_u64 v[42:43], s[0:1], 0, v[224:225]
	v_lshl_or_b32 v32, v0, 4, v32
	v_lshl_or_b32 v44, v0, 3, v44
	s_mov_b64 s[18:19], 0
	s_waitcnt vmcnt(0)
	v_mov_b64_e32 v[0:1], v[28:29]
	v_mov_b64_e32 v[2:3], v[30:31]
	v_mov_b64_e32 v[8:9], v[16:17]
	v_mov_b64_e32 v[10:11], v[18:19]
	v_mov_b64_e32 v[12:13], v[20:21]
	v_mov_b64_e32 v[14:15], v[22:23]
	v_mov_b64_e32 v[4:5], v[24:25]
	v_mov_b64_e32 v[6:7], v[26:27]
	s_branch .LBB0_368
.LBB0_367:
	s_or_b64 exec, exec, s[20:21]
	v_add_f32_e32 v50, v29, v28
	v_add_f32_e32 v50, v30, v50
	v_add_f32_e32 v51, v17, v16
	v_add_f32_e32 v50, v31, v50
	v_add_f32_e32 v51, v18, v51
	v_add_f32_e32 v50, 0, v50
	v_add_f32_e32 v51, v19, v51
	v_add_f32_e32 v50, v51, v50
	v_add_f32_e32 v51, v21, v20
	v_add_f32_e32 v51, v22, v51
	v_add_f32_e32 v51, v23, v51
	v_add_f32_e32 v50, v51, v50
	v_add_f32_e32 v51, v25, v24
	v_add_f32_e32 v51, v26, v51
	v_add_f32_e32 v51, v27, v51
	v_add_f32_e32 v50, v51, v50
	v_min_i32_e32 v48, 0x4000, v48
	v_ashrrev_i32_e32 v48, 11, v48
	v_add_f32_dpp v50, v50, v50 row_ror:8 row_mask:0xf bank_mask:0xf bound_ctrl:1
	v_mul_i32_i24_e32 v62, 0x2400, v48
	v_ashrrev_i32_e32 v63, 31, v62
	v_add_f32_dpp v50, v50, v50 row_ror:4 row_mask:0xf bank_mask:0xf bound_ctrl:1
	s_and_b64 s[0:1], exec, s[0:1]
	s_or_b64 s[18:19], s[0:1], s[18:19]
	v_add_f32_dpp v50, v50, v50 row_ror:2 row_mask:0xf bank_mask:0xf bound_ctrl:1
	v_lshl_add_u64 v[32:33], v[32:33], 0, s[68:69]
	s_nop 0
	v_add_f32_dpp v50, v50, v50 row_ror:1 row_mask:0xf bank_mask:0xf bound_ctrl:1
	v_mov_b32_e32 v51, v50
	s_nop 1
	v_permlane16_swap_b32_e32 v50, v51
	v_add_f32_e32 v50, v50, v51
	v_mov_b32_e32 v51, v50
	s_nop 1
	v_permlane32_swap_b32_e32 v50, v51
	v_add_f32_e32 v50, v50, v51
	v_mul_f32_e32 v54, 0x3a800000, v50
	v_pk_add_f32 v[64:65], v[28:29], v[54:55] op_sel_hi:[1,0] neg_lo:[0,1] neg_hi:[0,1]
	v_pk_add_f32 v[72:73], v[16:17], v[54:55] op_sel_hi:[1,0] neg_lo:[0,1] neg_hi:[0,1]
	v_pk_mul_f32 v[66:67], v[64:65], v[64:65]
	v_pk_add_f32 v[68:69], v[30:31], v[54:55] op_sel_hi:[1,0] neg_lo:[0,1] neg_hi:[0,1]
	v_pk_mul_f32 v[16:17], v[72:73], v[72:73]
	v_pk_add_f32 v[74:75], v[18:19], v[54:55] op_sel_hi:[1,0] neg_lo:[0,1] neg_hi:[0,1]
	v_pk_mul_f32 v[70:71], v[68:69], v[68:69]
	v_pk_mul_f32 v[18:19], v[74:75], v[74:75]
	v_add_f32_e32 v16, v16, v17
	v_add_f32_e32 v17, v66, v67
	v_pk_add_f32 v[76:77], v[20:21], v[54:55] op_sel_hi:[1,0] neg_lo:[0,1] neg_hi:[0,1]
	v_add_f32_e32 v16, v18, v16
	v_add_f32_e32 v17, v70, v17
	v_pk_mul_f32 v[20:21], v[76:77], v[76:77]
	v_pk_add_f32 v[78:79], v[22:23], v[54:55] op_sel_hi:[1,0] neg_lo:[0,1] neg_hi:[0,1]
	v_add_f32_e32 v16, v19, v16
	v_add_f32_e32 v17, v71, v17
	v_pk_mul_f32 v[22:23], v[78:79], v[78:79]
	v_add_f32_e32 v16, v17, v16
	v_add_f32_e32 v17, v20, v21
	v_pk_add_f32 v[80:81], v[24:25], v[54:55] op_sel_hi:[1,0] neg_lo:[0,1] neg_hi:[0,1]
	v_add_f32_e32 v17, v22, v17
	v_pk_mul_f32 v[24:25], v[80:81], v[80:81]
	v_pk_add_f32 v[54:55], v[26:27], v[54:55] op_sel_hi:[1,0] neg_lo:[0,1] neg_hi:[0,1]
	v_add_f32_e32 v17, v23, v17
	v_pk_mul_f32 v[26:27], v[54:55], v[54:55]
	v_add_f32_e32 v16, v17, v16
	v_add_f32_e32 v17, v24, v25
	v_add_f32_e32 v17, v26, v17
	v_add_f32_e32 v17, v27, v17
	v_add_f32_e32 v16, v17, v16
	v_lshlrev_b64 v[28:29], 2, v[62:63]
	v_lshl_add_u64 v[30:31], v[40:41], 0, v[28:29]
	v_add_f32_dpp v16, v16, v16 row_ror:8 row_mask:0xf bank_mask:0xf bound_ctrl:1
	v_lshl_add_u64 v[28:29], v[42:43], 0, v[28:29]
	v_lshl_add_u64 v[62:63], s[86:87], 0, v[44:45]
	v_add_f32_dpp v16, v16, v16 row_ror:4 row_mask:0xf bank_mask:0xf bound_ctrl:1
	v_lshl_add_u64 v[44:45], v[44:45], 0, s[42:43]
	s_nop 0
	v_add_f32_dpp v16, v16, v16 row_ror:2 row_mask:0xf bank_mask:0xf bound_ctrl:1
	s_nop 1
	v_add_f32_dpp v16, v16, v16 row_ror:1 row_mask:0xf bank_mask:0xf bound_ctrl:1
	v_mov_b32_e32 v17, v16
	s_nop 1
	v_permlane16_swap_b32_e32 v16, v17
	v_add_f32_e32 v16, v16, v17
	v_mov_b32_e32 v17, v16
	s_nop 1
	v_permlane32_swap_b32_e32 v16, v17
	v_add_f32_e32 v16, v16, v17
	v_fmamk_f32 v16, v16, 0x3a800000, v238
	v_cmp_gt_f32_e32 vcc, s49, v16
	v_mul_f32_e32 v17, 0x4b800000, v16
	s_nop 0
	v_cndmask_b32_e32 v16, v16, v17, vcc
	v_rsq_f32_e32 v16, v16
	s_nop 0
	v_mul_f32_e32 v17, 0x45800000, v16
	v_cndmask_b32_e32 v48, v16, v17, vcc
	v_add_co_u32_e32 v46, vcc, s88, v46
	s_nop 1
	v_addc_co_u32_e32 v47, vcc, 0, v47, vcc
	v_add_co_u32_e32 v50, vcc, s95, v62
	s_nop 1
	v_addc_co_u32_e32 v51, vcc, 0, v63, vcc
	s_waitcnt vmcnt(4)
; __device__ __forceinline__ void ln_phase(float* X, u16* H, const float* g, const float* b, const float* shift,
;                                          const float* scale, int M, float* outp, const float* part = nullptr) {
;     ...
;   for (int row = blockIdx.x * 8 + wid; row < M; row += GRID * 8) {
;     float4 v[4];
;     float* xr = X + (size_t)row * DM;
; #pragma unroll
;     for (int i = 0; i < 4; ++i) v[i] = nx[i];
;     {
;       const int nrow = row + GRID * 8;
;       if (nrow < M) {
; #pragma unroll
;         for (int i = 0; i < 4; ++i) nx[i] = *(const float4*)(X + (size_t)nrow * DM + i * 256 + lane * 4);
;       }
;     }
;     if (part != nullptr && row >= MLAT) {
; #pragma unroll
;       for (int i = 0; i < 4; ++i) {
;         const float4 p4 = *(const float4*)(part + (size_t)(row - MLAT) * DM + i * 256 + lane * 4);
;         v[i].x += p4.x; v[i].y += p4.y; v[i].z += p4.z; v[i].w += p4.w;
;       }
;     }
;     float s = 0.f;
; #pragma unroll
;     for (int i = 0; i < 4; ++i) s += v[i].x + v[i].y + v[i].z + v[i].w;
;     const float mu = wave_sum(s) * (1.0f / 1024.0f);
;     float q = 0.f;
; #pragma unroll
;     for (int i = 0; i < 4; ++i) {
;       v[i].x -= mu; v[i].y -= mu; v[i].z -= mu; v[i].w -= mu;
;       q += v[i].x * v[i].x + v[i].y * v[i].y + v[i].z * v[i].z + v[i].w * v[i].w;
;     }
;     const float rstd = rsqrtf(wave_sum(q) * (1.0f / 1024.0f) + EPS);
;     const int cv = row < MLAT ? (row >> 11) : 8;
; #pragma unroll
;     for (int i = 0; i < 4; ++i) {
;       const int col = i * 256 + lane * 4;
;       const float4 gg = *(const float4*)(g + col), bb = *(const float4*)(b + col);
;       float4 y;
;       y.x = v[i].x * rstd * gg.x + bb.x; y.y = v[i].y * rstd * gg.y + bb.y;
;       y.z = v[i].z * rstd * gg.z + bb.z; y.w = v[i].w * rstd * gg.w + bb.w;
;       if (outp) {
;         *(float4*)(outp + (size_t)row * DM + col) = y;
;       } else {
;         *(float4*)(xr + col) = y;
;         const float4 sh = *(const float4*)(shift + cv * 9216 + col), sc = *(const float4*)(scale + cv * 9216 + col);
;         u32x2 pk;
;         pk.x = pack2(y.x * (1.0f + sc.x) + sh.x, y.y * (1.0f + sc.y) + sh.y);
;         pk.y = pack2(y.z * (1.0f + sc.z) + sh.z, y.w * (1.0f + sc.w) + sh.w);
;         *(u32x2*)(H + (size_t)row * DM + col) = pk;
	v_pk_mul_f32 v[16:17], v[64:65], v[48:49] op_sel_hi:[1,0]
	v_pk_mul_f32 v[18:19], v[68:69], v[48:49] op_sel_hi:[1,0]
	v_pk_add_f32 v[100:101], v[100:101], 1.0 op_sel_hi:[1,0]
	v_pk_add_f32 v[102:103], v[102:103], 1.0 op_sel_hi:[1,0]
	v_pk_fma_f32 v[16:17], v[88:89], v[16:17], v[92:93]
	v_pk_fma_f32 v[18:19], v[90:91], v[18:19], v[94:95]
	global_store_dwordx4 v[46:47], v[16:19], off
	v_pk_fma_f32 v[20:21], v[16:17], v[100:101], v[96:97]
	v_pk_fma_f32 v[22:23], v[18:19], v[102:103], v[98:99]
	v_cvt_pk_bf16_f32 v20, v20, v21
	v_cvt_pk_bf16_f32 v21, v22, v23
	global_store_dwordx2 v[50:51], v[20:21], off
	v_pk_mul_f32 v[16:17], v[72:73], v[48:49] op_sel_hi:[1,0]
	v_pk_mul_f32 v[18:19], v[74:75], v[48:49] op_sel_hi:[1,0]
	v_pk_add_f32 v[116:117], v[116:117], 1.0 op_sel_hi:[1,0]
	v_pk_add_f32 v[118:119], v[118:119], 1.0 op_sel_hi:[1,0]
	v_pk_fma_f32 v[16:17], v[104:105], v[16:17], v[108:109]
	v_pk_fma_f32 v[18:19], v[106:107], v[18:19], v[110:111]
	global_store_dwordx4 v[46:47], v[16:19], off offset:1024
	v_pk_fma_f32 v[20:21], v[16:17], v[116:117], v[112:113]
	v_pk_fma_f32 v[22:23], v[18:19], v[118:119], v[114:115]
	v_cvt_pk_bf16_f32 v20, v20, v21
	v_cvt_pk_bf16_f32 v21, v22, v23
	global_store_dwordx2 v[50:51], v[20:21], off offset:512
	v_pk_mul_f32 v[16:17], v[76:77], v[48:49] op_sel_hi:[1,0]
	v_pk_mul_f32 v[18:19], v[78:79], v[48:49] op_sel_hi:[1,0]
	v_pk_add_f32 v[132:133], v[132:133], 1.0 op_sel_hi:[1,0]
	v_pk_add_f32 v[134:135], v[134:135], 1.0 op_sel_hi:[1,0]
	v_pk_fma_f32 v[16:17], v[120:121], v[16:17], v[124:125]
	v_pk_fma_f32 v[18:19], v[122:123], v[18:19], v[126:127]
	global_store_dwordx4 v[46:47], v[16:19], off offset:2048
	v_pk_fma_f32 v[20:21], v[16:17], v[132:133], v[128:129]
	v_pk_fma_f32 v[22:23], v[18:19], v[134:135], v[130:131]
	v_cvt_pk_bf16_f32 v20, v20, v21
	v_cvt_pk_bf16_f32 v21, v22, v23
	global_store_dwordx2 v[50:51], v[20:21], off offset:1024
	v_pk_mul_f32 v[16:17], v[80:81], v[48:49] op_sel_hi:[1,0]
	v_pk_mul_f32 v[18:19], v[54:55], v[48:49] op_sel_hi:[1,0]
	v_pk_add_f32 v[148:149], v[148:149], 1.0 op_sel_hi:[1,0]
	v_pk_add_f32 v[150:151], v[150:151], 1.0 op_sel_hi:[1,0]
	v_pk_fma_f32 v[16:17], v[136:137], v[16:17], v[140:141]
	v_pk_fma_f32 v[18:19], v[138:139], v[18:19], v[142:143]
	global_store_dwordx4 v[46:47], v[16:19], off offset:3072
	v_pk_fma_f32 v[20:21], v[16:17], v[148:149], v[144:145]
	v_pk_fma_f32 v[22:23], v[18:19], v[150:151], v[146:147]
	v_cvt_pk_bf16_f32 v20, v20, v21
	v_cvt_pk_bf16_f32 v21, v22, v23
	global_store_dwordx2 v[50:51], v[20:21], off offset:1536
	v_mov_b32_e32 v48, v49
	s_andn2_b64 exec, exec, s[18:19]
	s_cbranch_execz .LBB0_372
.LBB0_368:
	v_add_u32_e32 v49, 0x800, v48
	v_cmp_gt_i32_e32 vcc, s24, v49
	v_cmp_le_i32_e64 s[0:1], s24, v49
	v_lshl_add_u64 v[46:47], s[86:87], 0, v[32:33]
	s_waitcnt vmcnt(11)
	v_mov_b64_e32 v[28:29], v[0:1]
	v_mov_b64_e32 v[30:31], v[2:3]
	s_waitcnt vmcnt(10)
	v_mov_b64_e32 v[16:17], v[8:9]
	v_mov_b64_e32 v[18:19], v[10:11]
	s_waitcnt vmcnt(9)
	v_mov_b64_e32 v[20:21], v[12:13]
	v_mov_b64_e32 v[22:23], v[14:15]
	s_waitcnt vmcnt(8)
	v_mov_b64_e32 v[24:25], v[4:5]
	v_mov_b64_e32 v[26:27], v[6:7]
	v_min_i32_e32 v82, 0x4000, v48
	v_ashrrev_i32_e32 v82, 11, v82
	v_mul_i32_i24_e32 v82, 0x2400, v82
	v_ashrrev_i32_e32 v83, 31, v82
	v_lshlrev_b64 v[82:83], 2, v[82:83]
	v_lshl_add_u64 v[84:85], v[40:41], 0, v[82:83]
	v_lshl_add_u64 v[86:87], v[42:43], 0, v[82:83]
	global_load_dwordx4 v[88:91], v[36:37], off
	global_load_dwordx4 v[92:95], v[38:39], off
	global_load_dwordx4 v[96:99], v[84:85], off
	global_load_dwordx4 v[100:103], v[86:87], off
	global_load_dwordx4 v[104:107], v[36:37], off offset:1024
	global_load_dwordx4 v[108:111], v[38:39], off offset:1024
	global_load_dwordx4 v[112:115], v[84:85], off offset:1024
	global_load_dwordx4 v[116:119], v[86:87], off offset:1024
	global_load_dwordx4 v[120:123], v[36:37], off offset:2048
	global_load_dwordx4 v[124:127], v[38:39], off offset:2048
	global_load_dwordx4 v[128:131], v[84:85], off offset:2048
	global_load_dwordx4 v[132:135], v[86:87], off offset:2048
	global_load_dwordx4 v[136:139], v[36:37], off offset:3072
	global_load_dwordx4 v[140:143], v[38:39], off offset:3072
	global_load_dwordx4 v[144:147], v[84:85], off offset:3072
	global_load_dwordx4 v[148:151], v[86:87], off offset:3072
	s_mov_b64 s[20:21], exec
	v_add_co_u32_e32 v4, vcc, 0xad54000, v46
	s_nop 1
	v_addc_co_u32_e32 v5, vcc, 0, v47, vcc
	global_load_dwordx4 v[0:3], v[4:5], off
	global_load_dwordx4 v[8:11], v[4:5], off offset:1024
	global_load_dwordx4 v[12:15], v[4:5], off offset:2048
	s_nop 0
	global_load_dwordx4 v[4:7], v[4:5], off offset:3072

; __device__ __forceinline__ int otid() { int t = threadIdx.x; asm volatile("" : "+v"(t)); return t; }
; __device__ __forceinline__ void ln_phase(float* X, u16* H, const float* g, const float* b, const float* shift,
;                                          const float* scale, int M, float* outp, const float* part = nullptr) {
;   const int tid_ = otid(); const int wid = tid_ >> 6, lane = tid_ & 63;
;   float4 nx[4];
;   {
;     const int r0 = blockIdx.x * 8 + wid;
;     if (r0 < M) {
; #pragma unroll
;       for (int i = 0; i < 4; ++i) nx[i] = *(const float4*)(X + (size_t)r0 * DM + i * 256 + lane * 4);
;     }
;   }
;   for (int row = blockIdx.x * 8 + wid; row < M; row += GRID * 8) {
;     float4 v[4];
;     float* xr = X + (size_t)row * DM;
; #pragma unroll
;     for (int i = 0; i < 4; ++i) v[i] = nx[i];
;     {
;       const int nrow = row + GRID * 8;
;       if (nrow < M) {
; #pragma unroll
;         for (int i = 0; i < 4; ++i) nx[i] = *(const float4*)(X + (size_t)nrow * DM + i * 256 + lane * 4);
;       }
;     }
;     if (part != nullptr && row >= MLAT) {
; #pragma unroll
;       for (int i = 0; i < 4; ++i) {
;         const float4 p4 = *(const float4*)(part + (size_t)(row - MLAT) * DM + i * 256 + lane * 4);
;         v[i].x += p4.x; v[i].y += p4.y; v[i].z += p4.z; v[i].w += p4.w;
;       }
;     }
;     float s = 0.f;
; #pragma unroll
;     for (int i = 0; i < 4; ++i) s += v[i].x + v[i].y + v[i].z + v[i].w;
;     const float mu = wave_sum(s) * (1.0f / 1024.0f);
;     float q = 0.f;
; #pragma unroll
;     for (int i = 0; i < 4; ++i) {
;       v[i].x -= mu; v[i].y -= mu; v[i].z -= mu; v[i].w -= mu;
;       q += v[i].x * v[i].x + v[i].y * v[i].y + v[i].z * v[i].z + v[i].w * v[i].w;
;     }
;     const float rstd = rsqrtf(wave_sum(q) * (1.0f / 1024.0f) + EPS);
.LBB0_400:
	s_andn2_b64 vcc, exec, s[0:1]
	s_cbranch_vccnz .LBB0_409
	v_mov_b32_e32 v0, v228
	v_readlane_b32 s0, v254, 38
	v_ashrrev_i32_e32 v1, 6, v0
	v_readlane_b32 s1, v254, 39
	v_add_u32_e32 v48, s0, v1
	v_readlane_b32 s0, v255, 22
	s_nop 1
	v_cmp_gt_i32_e32 vcc, s0, v48
	s_and_saveexec_b64 s[6:7], vcc
	s_cbranch_execz .LBB0_408
	v_ashrrev_i32_e32 v49, 31, v48
	v_lshlrev_b64 v[32:33], 12, v[48:49]
	v_lshlrev_b32_e32 v1, 4, v0
	v_lshl_add_u64 v[2:3], s[36:37], 0, v[32:33]
	v_and_b32_e32 v224, 0x3f0, v1
	v_lshl_add_u64 v[2:3], v[2:3], 0, v[224:225]
	global_load_dwordx4 v[28:31], v[2:3], off
	global_load_dwordx4 v[16:19], v[2:3], off offset:1024
	global_load_dwordx4 v[20:23], v[2:3], off offset:2048
	global_load_dwordx4 v[24:27], v[2:3], off offset:3072
	v_readlane_b32 s0, v254, 54
	v_readlane_b32 s1, v254, 55
	v_and_b32_e32 v0, 63, v0
	v_lshlrev_b64 v[44:45], 11, v[48:49]
	v_lshl_add_u64 v[40:41], s[0:1], 0, v[224:225]
	v_readlane_b32 s0, v254, 56
	v_readlane_b32 s1, v254, 57
	v_lshl_add_u64 v[34:35], s[16:17], 0, v[224:225]
	v_lshl_add_u64 v[36:37], s[10:11], 0, v[224:225]
	v_lshl_add_u64 v[38:39], s[14:15], 0, v[224:225]
	v_lshl_add_u64 v[42:43], s[0:1], 0, v[224:225]
	v_lshl_or_b32 v32, v0, 4, v32
	v_lshl_or_b32 v44, v0, 3, v44
	s_mov_b64 s[10:11], 0
	s_waitcnt vmcnt(0)
	v_mov_b64_e32 v[0:1], v[28:29]
	v_mov_b64_e32 v[2:3], v[30:31]
	v_mov_b64_e32 v[8:9], v[16:17]
	v_mov_b64_e32 v[10:11], v[18:19]
	v_mov_b64_e32 v[12:13], v[20:21]
	v_mov_b64_e32 v[14:15], v[22:23]
	v_mov_b64_e32 v[4:5], v[24:25]
	v_mov_b64_e32 v[6:7], v[26:27]
	s_branch .LBB0_404
.LBB0_403:
	s_or_b64 exec, exec, s[14:15]
	v_add_f32_e32 v50, v29, v28
	v_add_f32_e32 v50, v30, v50
	v_add_f32_e32 v51, v17, v16
	v_add_f32_e32 v50, v31, v50
	v_add_f32_e32 v51, v18, v51
	v_add_f32_e32 v50, 0, v50
	v_add_f32_e32 v51, v19, v51
	v_add_f32_e32 v50, v51, v50
	v_add_f32_e32 v51, v21, v20
	v_add_f32_e32 v51, v22, v51
	v_add_f32_e32 v51, v23, v51
	v_add_f32_e32 v50, v51, v50
	v_add_f32_e32 v51, v25, v24
	v_add_f32_e32 v51, v26, v51
	v_add_f32_e32 v51, v27, v51
	v_add_f32_e32 v50, v51, v50
	v_min_i32_e32 v48, 0x4000, v48
	v_ashrrev_i32_e32 v48, 11, v48
	v_add_f32_dpp v50, v50, v50 row_ror:8 row_mask:0xf bank_mask:0xf bound_ctrl:1
	v_mul_i32_i24_e32 v62, 0x2400, v48
	v_ashrrev_i32_e32 v63, 31, v62
	v_add_f32_dpp v50, v50, v50 row_ror:4 row_mask:0xf bank_mask:0xf bound_ctrl:1
	s_and_b64 s[0:1], exec, s[0:1]
	s_or_b64 s[10:11], s[0:1], s[10:11]
	v_add_f32_dpp v50, v50, v50 row_ror:2 row_mask:0xf bank_mask:0xf bound_ctrl:1
	v_lshl_add_u64 v[32:33], v[32:33], 0, s[68:69]
	s_nop 0
	v_add_f32_dpp v50, v50, v50 row_ror:1 row_mask:0xf bank_mask:0xf bound_ctrl:1
	v_mov_b32_e32 v51, v50
	s_nop 1
	v_permlane16_swap_b32_e32 v50, v51
	v_add_f32_e32 v50, v50, v51
	v_mov_b32_e32 v51, v50
	s_nop 1
	v_permlane32_swap_b32_e32 v50, v51
	v_add_f32_e32 v50, v50, v51
	v_mul_f32_e32 v54, 0x3a800000, v50
	v_pk_add_f32 v[64:65], v[28:29], v[54:55] op_sel_hi:[1,0] neg_lo:[0,1] neg_hi:[0,1]
	v_pk_add_f32 v[72:73], v[16:17], v[54:55] op_sel_hi:[1,0] neg_lo:[0,1] neg_hi:[0,1]
	v_pk_mul_f32 v[66:67], v[64:65], v[64:65]
	v_pk_add_f32 v[68:69], v[30:31], v[54:55] op_sel_hi:[1,0] neg_lo:[0,1] neg_hi:[0,1]
	v_pk_mul_f32 v[16:17], v[72:73], v[72:73]
	v_pk_add_f32 v[74:75], v[18:19], v[54:55] op_sel_hi:[1,0] neg_lo:[0,1] neg_hi:[0,1]
	v_pk_mul_f32 v[70:71], v[68:69], v[68:69]
	v_pk_mul_f32 v[18:19], v[74:75], v[74:75]
	v_add_f32_e32 v16, v16, v17
	v_add_f32_e32 v17, v66, v67
	v_pk_add_f32 v[76:77], v[20:21], v[54:55] op_sel_hi:[1,0] neg_lo:[0,1] neg_hi:[0,1]
	v_add_f32_e32 v16, v18, v16
	v_add_f32_e32 v17, v70, v17
	v_pk_mul_f32 v[20:21], v[76:77], v[76:77]
	v_pk_add_f32 v[78:79], v[22:23], v[54:55] op_sel_hi:[1,0] neg_lo:[0,1] neg_hi:[0,1]
	v_add_f32_e32 v16, v19, v16
	v_add_f32_e32 v17, v71, v17
	v_pk_mul_f32 v[22:23], v[78:79], v[78:79]
	v_add_f32_e32 v16, v17, v16
	v_add_f32_e32 v17, v20, v21
	v_pk_add_f32 v[80:81], v[24:25], v[54:55] op_sel_hi:[1,0] neg_lo:[0,1] neg_hi:[0,1]
	v_add_f32_e32 v17, v22, v17
	v_pk_mul_f32 v[24:25], v[80:81], v[80:81]
	v_pk_add_f32 v[54:55], v[26:27], v[54:55] op_sel_hi:[1,0] neg_lo:[0,1] neg_hi:[0,1]
	v_add_f32_e32 v17, v23, v17
	v_pk_mul_f32 v[26:27], v[54:55], v[54:55]
	v_add_f32_e32 v16, v17, v16
	v_add_f32_e32 v17, v24, v25
	v_add_f32_e32 v17, v26, v17
	v_add_f32_e32 v17, v27, v17
	v_add_f32_e32 v16, v17, v16
	v_lshlrev_b64 v[28:29], 2, v[62:63]
	v_lshl_add_u64 v[30:31], v[40:41], 0, v[28:29]
	v_add_f32_dpp v16, v16, v16 row_ror:8 row_mask:0xf bank_mask:0xf bound_ctrl:1
	v_lshl_add_u64 v[28:29], v[42:43], 0, v[28:29]
	v_lshl_add_u64 v[62:63], s[86:87], 0, v[44:45]
	v_add_f32_dpp v16, v16, v16 row_ror:4 row_mask:0xf bank_mask:0xf bound_ctrl:1
	v_lshl_add_u64 v[44:45], v[44:45], 0, s[42:43]
	s_nop 0
	v_add_f32_dpp v16, v16, v16 row_ror:2 row_mask:0xf bank_mask:0xf bound_ctrl:1
	s_nop 1
	v_add_f32_dpp v16, v16, v16 row_ror:1 row_mask:0xf bank_mask:0xf bound_ctrl:1
	v_mov_b32_e32 v17, v16
	s_nop 1
	v_permlane16_swap_b32_e32 v16, v17
	v_add_f32_e32 v16, v16, v17
	v_mov_b32_e32 v17, v16
	s_nop 1
	v_permlane32_swap_b32_e32 v16, v17
	v_add_f32_e32 v16, v16, v17
	v_fmamk_f32 v16, v16, 0x3a800000, v238
	v_cmp_gt_f32_e32 vcc, s49, v16
	v_mul_f32_e32 v17, 0x4b800000, v16
	s_nop 0
	v_cndmask_b32_e32 v16, v16, v17, vcc
	v_rsq_f32_e32 v16, v16
	s_nop 0
	v_mul_f32_e32 v17, 0x45800000, v16
	v_cndmask_b32_e32 v48, v16, v17, vcc
	v_add_co_u32_e32 v46, vcc, s88, v46
	s_nop 1
	v_addc_co_u32_e32 v47, vcc, 0, v47, vcc
	v_add_co_u32_e32 v50, vcc, s95, v62
	s_nop 1
	v_addc_co_u32_e32 v51, vcc, 0, v63, vcc
	s_waitcnt vmcnt(4)
; __device__ __forceinline__ void ln_phase(float* X, u16* H, const float* g, const float* b, const float* shift,
;                                          const float* scale, int M, float* outp, const float* part = nullptr) {
;     ...
;   for (int row = blockIdx.x * 8 + wid; row < M; row += GRID * 8) {
;     float4 v[4];
;     float* xr = X + (size_t)row * DM;
; #pragma unroll
;     for (int i = 0; i < 4; ++i) v[i] = nx[i];
;     {
;       const int nrow = row + GRID * 8;
;       if (nrow < M) {
; #pragma unroll
;         for (int i = 0; i < 4; ++i) nx[i] = *(const float4*)(X + (size_t)nrow * DM + i * 256 + lane * 4);
;       }
;     }
;     if (part != nullptr && row >= MLAT) {
; #pragma unroll
;       for (int i = 0; i < 4; ++i) {
;         const float4 p4 = *(const float4*)(part + (size_t)(row - MLAT) * DM + i * 256 + lane * 4);
;         v[i].x += p4.x; v[i].y += p4.y; v[i].z += p4.z; v[i].w += p4.w;
;       }
;     }
;     float s = 0.f;
; #pragma unroll
;     for (int i = 0; i < 4; ++i) s += v[i].x + v[i].y + v[i].z + v[i].w;
;     const float mu = wave_sum(s) * (1.0f / 1024.0f);
;     float q = 0.f;
; #pragma unroll
;     for (int i = 0; i < 4; ++i) {
;       v[i].x -= mu; v[i].y -= mu; v[i].z -= mu; v[i].w -= mu;
;       q += v[i].x * v[i].x + v[i].y * v[i].y + v[i].z * v[i].z + v[i].w * v[i].w;
;     }
;     const float rstd = rsqrtf(wave_sum(q) * (1.0f / 1024.0f) + EPS);
;     const int cv = row < MLAT ? (row >> 11) : 8;
; #pragma unroll
;     for (int i = 0; i < 4; ++i) {
;       const int col = i * 256 + lane * 4;
;       const float4 gg = *(const float4*)(g + col), bb = *(const float4*)(b + col);
;       float4 y;
;       y.x = v[i].x * rstd * gg.x + bb.x; y.y = v[i].y * rstd * gg.y + bb.y;
;       y.z = v[i].z * rstd * gg.z + bb.z; y.w = v[i].w * rstd * gg.w + bb.w;
;       if (outp) {
;         *(float4*)(outp + (size_t)row * DM + col) = y;
;       } else {
;         *(float4*)(xr + col) = y;
;         const float4 sh = *(const float4*)(shift + cv * 9216 + col), sc = *(const float4*)(scale + cv * 9216 + col);
;         u32x2 pk;
;         pk.x = pack2(y.x * (1.0f + sc.x) + sh.x, y.y * (1.0f + sc.y) + sh.y);
;         pk.y = pack2(y.z * (1.0f + sc.z) + sh.z, y.w * (1.0f + sc.w) + sh.w);
;         *(u32x2*)(H + (size_t)row * DM + col) = pk;
	v_pk_mul_f32 v[16:17], v[64:65], v[48:49] op_sel_hi:[1,0]
	v_pk_mul_f32 v[18:19], v[68:69], v[48:49] op_sel_hi:[1,0]
	v_pk_add_f32 v[100:101], v[100:101], 1.0 op_sel_hi:[1,0]
	v_pk_add_f32 v[102:103], v[102:103], 1.0 op_sel_hi:[1,0]
	v_pk_fma_f32 v[16:17], v[88:89], v[16:17], v[92:93]
	v_pk_fma_f32 v[18:19], v[90:91], v[18:19], v[94:95]
	global_store_dwordx4 v[46:47], v[16:19], off
	v_pk_fma_f32 v[20:21], v[16:17], v[100:101], v[96:97]
	v_pk_fma_f32 v[22:23], v[18:19], v[102:103], v[98:99]
	v_cvt_pk_bf16_f32 v20, v20, v21
	v_cvt_pk_bf16_f32 v21, v22, v23
	global_store_dwordx2 v[50:51], v[20:21], off
	v_pk_mul_f32 v[16:17], v[72:73], v[48:49] op_sel_hi:[1,0]
	v_pk_mul_f32 v[18:19], v[74:75], v[48:49] op_sel_hi:[1,0]
	v_pk_add_f32 v[116:117], v[116:117], 1.0 op_sel_hi:[1,0]
	v_pk_add_f32 v[118:119], v[118:119], 1.0 op_sel_hi:[1,0]
	v_pk_fma_f32 v[16:17], v[104:105], v[16:17], v[108:109]
	v_pk_fma_f32 v[18:19], v[106:107], v[18:19], v[110:111]
	global_store_dwordx4 v[46:47], v[16:19], off offset:1024
	v_pk_fma_f32 v[20:21], v[16:17], v[116:117], v[112:113]
	v_pk_fma_f32 v[22:23], v[18:19], v[118:119], v[114:115]
	v_cvt_pk_bf16_f32 v20, v20, v21
	v_cvt_pk_bf16_f32 v21, v22, v23
	global_store_dwordx2 v[50:51], v[20:21], off offset:512
	v_pk_mul_f32 v[16:17], v[76:77], v[48:49] op_sel_hi:[1,0]
	v_pk_mul_f32 v[18:19], v[78:79], v[48:49] op_sel_hi:[1,0]
	v_pk_add_f32 v[132:133], v[132:133], 1.0 op_sel_hi:[1,0]
	v_pk_add_f32 v[134:135], v[134:135], 1.0 op_sel_hi:[1,0]
	v_pk_fma_f32 v[16:17], v[120:121], v[16:17], v[124:125]
	v_pk_fma_f32 v[18:19], v[122:123], v[18:19], v[126:127]
	global_store_dwordx4 v[46:47], v[16:19], off offset:2048
	v_pk_fma_f32 v[20:21], v[16:17], v[132:133], v[128:129]
	v_pk_fma_f32 v[22:23], v[18:19], v[134:135], v[130:131]
	v_cvt_pk_bf16_f32 v20, v20, v21
	v_cvt_pk_bf16_f32 v21, v22, v23
	global_store_dwordx2 v[50:51], v[20:21], off offset:1024
	v_pk_mul_f32 v[16:17], v[80:81], v[48:49] op_sel_hi:[1,0]
	v_pk_mul_f32 v[18:19], v[54:55], v[48:49] op_sel_hi:[1,0]
	v_pk_add_f32 v[148:149], v[148:149], 1.0 op_sel_hi:[1,0]
	v_pk_add_f32 v[150:151], v[150:151], 1.0 op_sel_hi:[1,0]
	v_pk_fma_f32 v[16:17], v[136:137], v[16:17], v[140:141]
	v_pk_fma_f32 v[18:19], v[138:139], v[18:19], v[142:143]
	global_store_dwordx4 v[46:47], v[16:19], off offset:3072
	v_pk_fma_f32 v[20:21], v[16:17], v[148:149], v[144:145]
	v_pk_fma_f32 v[22:23], v[18:19], v[150:151], v[146:147]
	v_cvt_pk_bf16_f32 v20, v20, v21
	v_cvt_pk_bf16_f32 v21, v22, v23
	global_store_dwordx2 v[50:51], v[20:21], off offset:1536
	v_mov_b32_e32 v48, v49
	s_andn2_b64 exec, exec, s[10:11]
	s_cbranch_execz .LBB0_408
.LBB0_404:
	v_add_u32_e32 v49, 0x800, v48
	v_cmp_gt_i32_e32 vcc, s24, v49
	v_cmp_le_i32_e64 s[0:1], s24, v49
	v_lshl_add_u64 v[46:47], s[86:87], 0, v[32:33]
	s_waitcnt vmcnt(11)
	v_mov_b64_e32 v[28:29], v[0:1]
	v_mov_b64_e32 v[30:31], v[2:3]
	s_waitcnt vmcnt(10)
	v_mov_b64_e32 v[16:17], v[8:9]
	v_mov_b64_e32 v[18:19], v[10:11]
	s_waitcnt vmcnt(9)
	v_mov_b64_e32 v[20:21], v[12:13]
	v_mov_b64_e32 v[22:23], v[14:15]
	s_waitcnt vmcnt(8)
	v_mov_b64_e32 v[24:25], v[4:5]
	v_mov_b64_e32 v[26:27], v[6:7]
	v_min_i32_e32 v82, 0x4000, v48
	v_ashrrev_i32_e32 v82, 11, v82
	v_mul_i32_i24_e32 v82, 0x2400, v82
	v_ashrrev_i32_e32 v83, 31, v82
	v_lshlrev_b64 v[82:83], 2, v[82:83]
	v_lshl_add_u64 v[84:85], v[40:41], 0, v[82:83]
	v_lshl_add_u64 v[86:87], v[42:43], 0, v[82:83]
	global_load_dwordx4 v[88:91], v[36:37], off
	global_load_dwordx4 v[92:95], v[38:39], off
	global_load_dwordx4 v[96:99], v[84:85], off
	global_load_dwordx4 v[100:103], v[86:87], off
	global_load_dwordx4 v[104:107], v[36:37], off offset:1024
	global_load_dwordx4 v[108:111], v[38:39], off offset:1024
	global_load_dwordx4 v[112:115], v[84:85], off offset:1024
	global_load_dwordx4 v[116:119], v[86:87], off offset:1024
	global_load_dwordx4 v[120:123], v[36:37], off offset:2048
	global_load_dwordx4 v[124:127], v[38:39], off offset:2048
	global_load_dwordx4 v[128:131], v[84:85], off offset:2048
	global_load_dwordx4 v[132:135], v[86:87], off offset:2048
	global_load_dwordx4 v[136:139], v[36:37], off offset:3072
	global_load_dwordx4 v[140:143], v[38:39], off offset:3072
	global_load_dwordx4 v[144:147], v[84:85], off offset:3072
	global_load_dwordx4 v[148:151], v[86:87], off offset:3072
	s_mov_b64 s[14:15], exec
	v_add_co_u32_e32 v4, vcc, 0xad54000, v46
	s_nop 1
	v_addc_co_u32_e32 v5, vcc, 0, v47, vcc
	global_load_dwordx4 v[0:3], v[4:5], off
	global_load_dwordx4 v[8:11], v[4:5], off offset:1024
	global_load_dwordx4 v[12:15], v[4:5], off offset:2048
	s_nop 0
	global_load_dwordx4 v[4:7], v[4:5], off offset:3072

; #define WAIT_V(n) asm volatile("s_waitcnt vmcnt(%0)" ::"n"(n) : "memory")
;     ...
;     f32x4 acc[MT][4];
; #pragma unroll
;     for (int m = 0; m < MT; ++m)
; #pragma unroll
;       for (int n = 0; n < 4; ++n) acc[m][n] = f32x4{0.f, 0.f, 0.f, 0.f};
;     for (int t = 0; t < nt; ++t) {
;       const int cur = t & 1;
;       const char* sa = shm + cur * STAGE_B;
;       const char* sn = shm + (cur ^ 1) * STAGE_B;
;       const bool more = (t + 1 < nt) || (nitem < ntiles);
; #pragma unroll
;       for (int ks = 0; ks < 2; ++ks) {
; #pragma unroll
;         for (int p = 0; p < NP; ++p) {
;           const int q = ks * NP + p;
;           acc[p * 2][0] = __builtin_amdgcn_mfma_f32_16x16x32_bf16(Bq[BDBL ? ks : 0][0], Aq[q & 1][0], acc[p * 2][0], 0, 0, 0);
;           __builtin_amdgcn_sched_barrier(0);
;           if (q == 2 * NP - 1) {
;             WAIT_V(0);
;             __syncthreads();
;             if (more) {
;               if constexpr (BDBL) {
; #pragma unroll
;                 for (int n = 0; n < 4; ++n) Bq[0][n] = *(const bf16x8*)(sn + boff + (n * 2 + 0) * 1024);
;               }
; #pragma unroll
;               for (int i = 0; i < 2; ++i) Aq[0][i] = *(const bf16x8*)(sn + aoff + (i * 2 + 0) * 1024);
;             }
;           } else if (p + 1 < NP) {
; #pragma unroll
;             for (int i = 0; i < 2; ++i) Aq[(q + 1) & 1][i] = *(const bf16x8*)(sa + aoff + (((p + 1) * 2 + i) * 2 + ks) * 1024);
;           } else {
;             if constexpr (BDBL) {
; #pragma unroll
;               for (int n = 0; n < 4; ++n) Bq[1][n] = *(const bf16x8*)(sa + boff + (n * 2 + 1) * 1024);
;             }
; #pragma unroll
;             for (int i = 0; i < 2; ++i) Aq[(q + 1) & 1][i] = *(const bf16x8*)(sa + aoff + (i * 2 + 1) * 1024);
;           }
;           __builtin_amdgcn_sched_barrier(0);
; #pragma unroll
;           for (int i = 0; i < 2; ++i)
; #pragma unroll
;             for (int n = 0; n < 4; ++n)
;               if (i + n > 0)
;                 acc[p * 2 + i][n] = __builtin_amdgcn_mfma_f32_16x16x32_bf16(Bq[BDBL ? ks : 0][n], Aq[q & 1][i], acc[p * 2 + i][n], 0, 0, 0);
;           __builtin_amdgcn_sched_barrier(0);
;           if (q == GLDS_AT) {
;             if (t + 1 < nt) GLDS_STAGE(cur ^ 1, t + 1, Ab, Bb);
;             else if (nitem < ntiles) GLDS_STAGE(0, 0, nAb, nBb);
;             __builtin_amdgcn_sched_barrier(0);
;           }
.LBB0_458:
	v_lshl_add_u64 v[152:153], s[16:17], 0, v[226:227]
	v_lshl_add_u64 v[154:155], s[14:15], 0, v[226:227]
	s_mov_b64 s[0:1], 0
	s_waitcnt lgkmcnt(0)
	s_nop 0
	v_mfma_f32_16x16x32_bf16 v[148:151], v[12:15], v[20:23], 0
	s_and_b32 s14, s22, 0x10000
	s_xor_b32 s15, s14, 0x10000
	v_add_u32_e32 v184, s14, v241
	v_or_b32_e32 v176, s14, v242
	v_bitop3_b32 v185, s22, v242, v233 bitop3:0xce
	v_add_u32_e32 v186, s15, v241
	ds_read_b128 v[156:159], v184 offset:4096
	ds_read_b128 v[160:163], v184 offset:6144
	v_mfma_f32_16x16x32_bf16 v[144:147], v[8:11], v[20:23], 0
	s_add_i32 s14, s15, s4
	v_lshl_add_u64 v[180:181], v[152:153], 0, s[0:1]
	v_mfma_f32_16x16x32_bf16 v[140:143], v[4:7], v[20:23], 0
	v_lshl_add_u64 v[182:183], v[180:181], 0, s[38:39]
	s_mov_b32 m0, s14
	v_mfma_f32_16x16x32_bf16 v[20:23], v[0:3], v[20:23], 0
	s_add_i32 s15, s14, 0x8000
	global_load_lds_dwordx4 v[182:183], off
	v_mfma_f32_16x16x32_bf16 v[132:135], v[12:15], v[16:19], 0
	v_lshl_add_u64 v[182:183], v[180:181], 0, s[82:83]
	s_add_i32 m0, s14, 0x2000
	v_mfma_f32_16x16x32_bf16 v[128:131], v[8:11], v[16:19], 0
	global_load_lds_dwordx4 v[182:183], off
	v_lshl_add_u64 v[182:183], v[180:181], 0, s[78:79]
	v_mfma_f32_16x16x32_bf16 v[124:127], v[4:7], v[16:19], 0
	s_add_i32 m0, s14, 0x4000
	v_lshl_add_u64 v[180:181], v[180:181], 0, s[2:3]
	v_mfma_f32_16x16x32_bf16 v[16:19], v[0:3], v[16:19], 0
	global_load_lds_dwordx4 v[182:183], off
	s_add_i32 m0, s14, 0x6000
	s_waitcnt lgkmcnt(1)
	v_mfma_f32_16x16x32_bf16 v[116:119], v[12:15], v[156:159], 0
	s_nop 0
	ds_read_b128 v[120:123], v184 offset:8192
	ds_read_b128 v[136:139], v184 offset:10240
	global_load_lds_dwordx4 v[180:181], off
	v_lshl_add_u64 v[180:181], v[154:155], 0, s[0:1]
	v_mfma_f32_16x16x32_bf16 v[112:115], v[8:11], v[156:159], 0
	v_lshl_add_u64 v[182:183], v[180:181], 0, s[38:39]
	s_mov_b32 m0, s15
	v_mfma_f32_16x16x32_bf16 v[108:111], v[4:7], v[156:159], 0
	global_load_lds_dwordx4 v[182:183], off
	v_lshl_add_u64 v[182:183], v[180:181], 0, s[82:83]
	v_mfma_f32_16x16x32_bf16 v[104:107], v[0:3], v[156:159], 0
	s_add_i32 m0, s14, 0xa000
	s_waitcnt lgkmcnt(2)
	v_mfma_f32_16x16x32_bf16 v[100:103], v[12:15], v[160:163], 0
	global_load_lds_dwordx4 v[182:183], off
	v_lshl_add_u64 v[182:183], v[180:181], 0, s[78:79]
	v_mfma_f32_16x16x32_bf16 v[96:99], v[8:11], v[160:163], 0
	s_add_i32 m0, s14, 0xc000
	v_lshl_add_u64 v[180:181], v[180:181], 0, s[2:3]
	v_mfma_f32_16x16x32_bf16 v[92:95], v[4:7], v[160:163], 0
	global_load_lds_dwordx4 v[182:183], off
	s_add_i32 m0, s14, 0xe000
	v_mfma_f32_16x16x32_bf16 v[88:91], v[0:3], v[160:163], 0
	global_load_lds_dwordx4 v[180:181], off
	s_waitcnt lgkmcnt(1)
	v_mfma_f32_16x16x32_bf16 v[84:87], v[12:15], v[120:123], 0
	ds_read_b128 v[156:159], v184 offset:12288
	ds_read_b128 v[160:163], v184 offset:14336
	v_mfma_f32_16x16x32_bf16 v[80:83], v[8:11], v[120:123], 0
	v_mfma_f32_16x16x32_bf16 v[76:79], v[4:7], v[120:123], 0
	v_mfma_f32_16x16x32_bf16 v[72:75], v[0:3], v[120:123], 0
	s_waitcnt lgkmcnt(2)
	v_mfma_f32_16x16x32_bf16 v[68:71], v[12:15], v[136:139], 0
	v_mfma_f32_16x16x32_bf16 v[64:67], v[8:11], v[136:139], 0
	v_mfma_f32_16x16x32_bf16 v[60:63], v[4:7], v[136:139], 0
	v_mfma_f32_16x16x32_bf16 v[56:59], v[0:3], v[136:139], 0
	s_waitcnt lgkmcnt(1)
	v_mfma_f32_16x16x32_bf16 v[52:55], v[12:15], v[156:159], 0
	ds_read_b128 v[164:167], v176 offset:33792
	ds_read_b128 v[168:171], v176 offset:35840
	ds_read_b128 v[172:175], v176 offset:37888
	ds_read_b128 v[176:179], v176 offset:39936
	ds_read_b128 v[120:123], v184 offset:1024
	ds_read_b128 v[180:183], v184 offset:3072
	v_mfma_f32_16x16x32_bf16 v[48:51], v[8:11], v[156:159], 0
	v_mfma_f32_16x16x32_bf16 v[44:47], v[4:7], v[156:159], 0
	v_mfma_f32_16x16x32_bf16 v[40:43], v[0:3], v[156:159], 0
	s_waitcnt lgkmcnt(6)
	v_mfma_f32_16x16x32_bf16 v[36:39], v[12:15], v[160:163], 0
	v_mfma_f32_16x16x32_bf16 v[32:35], v[8:11], v[160:163], 0
	v_mfma_f32_16x16x32_bf16 v[28:31], v[4:7], v[160:163], 0
	v_mfma_f32_16x16x32_bf16 v[24:27], v[0:3], v[160:163], 0
	s_waitcnt lgkmcnt(0)
	v_mfma_f32_16x16x32_bf16 v[148:151], v[164:167], v[120:123], v[148:151]
	ds_read_b128 v[0:3], v184 offset:5120
	ds_read_b128 v[4:7], v184 offset:7168
	v_mfma_f32_16x16x32_bf16 v[144:147], v[168:171], v[120:123], v[144:147]
	v_mfma_f32_16x16x32_bf16 v[140:143], v[172:175], v[120:123], v[140:143]
	v_mfma_f32_16x16x32_bf16 v[136:139], v[176:179], v[120:123], v[20:23]
	v_mfma_f32_16x16x32_bf16 v[132:135], v[164:167], v[180:183], v[132:135]
	v_mfma_f32_16x16x32_bf16 v[128:131], v[168:171], v[180:183], v[128:131]
	v_mfma_f32_16x16x32_bf16 v[124:127], v[172:175], v[180:183], v[124:127]
	v_mfma_f32_16x16x32_bf16 v[120:123], v[176:179], v[180:183], v[16:19]
	s_waitcnt lgkmcnt(1)
	v_mfma_f32_16x16x32_bf16 v[116:119], v[164:167], v[0:3], v[116:119]
	ds_read_b128 v[8:11], v184 offset:9216
	ds_read_b128 v[12:15], v184 offset:11264
	v_mfma_f32_16x16x32_bf16 v[112:115], v[168:171], v[0:3], v[112:115]
	v_mfma_f32_16x16x32_bf16 v[108:111], v[172:175], v[0:3], v[108:111]
	v_mfma_f32_16x16x32_bf16 v[104:107], v[176:179], v[0:3], v[104:107]
	s_waitcnt lgkmcnt(2)
	v_mfma_f32_16x16x32_bf16 v[100:103], v[164:167], v[4:7], v[100:103]
	v_mfma_f32_16x16x32_bf16 v[96:99], v[168:171], v[4:7], v[96:99]
	v_mfma_f32_16x16x32_bf16 v[92:95], v[172:175], v[4:7], v[92:95]
	v_mfma_f32_16x16x32_bf16 v[88:91], v[176:179], v[4:7], v[88:91]
	s_waitcnt lgkmcnt(1)
	v_mfma_f32_16x16x32_bf16 v[84:87], v[164:167], v[8:11], v[84:87]
	ds_read_b128 v[156:159], v184 offset:13312
	ds_read_b128 v[160:163], v184 offset:15360
	v_mfma_f32_16x16x32_bf16 v[80:83], v[168:171], v[8:11], v[80:83]
	v_mfma_f32_16x16x32_bf16 v[76:79], v[172:175], v[8:11], v[76:79]
	v_mfma_f32_16x16x32_bf16 v[72:75], v[176:179], v[8:11], v[72:75]
	s_waitcnt lgkmcnt(2)
	v_mfma_f32_16x16x32_bf16 v[68:71], v[164:167], v[12:15], v[68:71]
	v_mfma_f32_16x16x32_bf16 v[64:67], v[168:171], v[12:15], v[64:67]
	v_mfma_f32_16x16x32_bf16 v[60:63], v[172:175], v[12:15], v[60:63]
	v_mfma_f32_16x16x32_bf16 v[56:59], v[176:179], v[12:15], v[56:59]
	s_waitcnt lgkmcnt(1)
	v_mfma_f32_16x16x32_bf16 v[52:55], v[164:167], v[156:159], v[52:55]
	s_waitcnt vmcnt(0)
	s_waitcnt lgkmcnt(0)
	s_barrier
	ds_read_b128 v[12:15], v185 offset:32768
	ds_read_b128 v[8:11], v185 offset:34816
	ds_read_b128 v[4:7], v185 offset:36864
	ds_read_b128 v[0:3], v185 offset:38912
	ds_read_b128 v[20:23], v186
	ds_read_b128 v[16:19], v186 offset:2048
	v_mfma_f32_16x16x32_bf16 v[48:51], v[168:171], v[156:159], v[48:51]
	v_mfma_f32_16x16x32_bf16 v[44:47], v[172:175], v[156:159], v[44:47]
	v_mfma_f32_16x16x32_bf16 v[40:43], v[176:179], v[156:159], v[40:43]
	v_mfma_f32_16x16x32_bf16 v[36:39], v[164:167], v[160:163], v[36:39]
	v_mfma_f32_16x16x32_bf16 v[32:35], v[168:171], v[160:163], v[32:35]
	v_mfma_f32_16x16x32_bf16 v[28:31], v[172:175], v[160:163], v[28:31]
	v_mfma_f32_16x16x32_bf16 v[24:27], v[176:179], v[160:163], v[24:27]
	s_add_u32 s0, s0, 0x80
	s_addc_u32 s1, s1, 0
	s_add_i32 s22, s22, 0x10000

;     ...
;     f32x4 acc[MT][4];
; #pragma unroll
;     for (int m = 0; m < MT; ++m)
; #pragma unroll
;       for (int n = 0; n < 4; ++n) acc[m][n] = f32x4{0.f, 0.f, 0.f, 0.f};
;     for (int t = 0; t < nt; ++t) {
;       const int cur = t & 1;
;       const char* sa = shm + cur * STAGE_B;
;       const char* sn = shm + (cur ^ 1) * STAGE_B;
;       const bool more = (t + 1 < nt) || (nitem < ntiles);
; #pragma unroll
;       for (int ks = 0; ks < 2; ++ks) {
; #pragma unroll
;         for (int p = 0; p < NP; ++p) {
;           const int q = ks * NP + p;
;           acc[p * 2][0] = __builtin_amdgcn_mfma_f32_16x16x32_bf16(Bq[BDBL ? ks : 0][0], Aq[q & 1][0], acc[p * 2][0], 0, 0, 0);
;           __builtin_amdgcn_sched_barrier(0);
;           if (q == 2 * NP - 1) {
;             WAIT_V(0);
;             __syncthreads();
;             if (more) {
;               if constexpr (BDBL) {
; #pragma unroll
;                 for (int n = 0; n < 4; ++n) Bq[0][n] = *(const bf16x8*)(sn + boff + (n * 2 + 0) * 1024);
;               }
; #pragma unroll
;               for (int i = 0; i < 2; ++i) Aq[0][i] = *(const bf16x8*)(sn + aoff + (i * 2 + 0) * 1024);
;             }
;           } else if (p + 1 < NP) {
; #pragma unroll
;             for (int i = 0; i < 2; ++i) Aq[(q + 1) & 1][i] = *(const bf16x8*)(sa + aoff + (((p + 1) * 2 + i) * 2 + ks) * 1024);
;           } else {
;             if constexpr (BDBL) {
; #pragma unroll
;               for (int n = 0; n < 4; ++n) Bq[1][n] = *(const bf16x8*)(sa + boff + (n * 2 + 1) * 1024);
;             }
; #pragma unroll
;             for (int i = 0; i < 2; ++i) Aq[(q + 1) & 1][i] = *(const bf16x8*)(sa + aoff + (i * 2 + 1) * 1024);
;           }
;           __builtin_amdgcn_sched_barrier(0);
; #pragma unroll
;           for (int i = 0; i < 2; ++i)
; #pragma unroll
;             for (int n = 0; n < 4; ++n)
;               if (i + n > 0)
;                 acc[p * 2 + i][n] = __builtin_amdgcn_mfma_f32_16x16x32_bf16(Bq[BDBL ? ks : 0][n], Aq[q & 1][i], acc[p * 2 + i][n], 0, 0, 0);
;           __builtin_amdgcn_sched_barrier(0);
;           if (q == GLDS_AT) {
;             if (t + 1 < nt) GLDS_STAGE(cur ^ 1, t + 1, Ab, Bb);
;             else if (nitem < ntiles) GLDS_STAGE(0, 0, nAb, nBb);
;             __builtin_amdgcn_sched_barrier(0);
;           }
;           if constexpr (!BDBL) {
;             if (p + 1 == NP) {
;               if (ks == 0) {
.LBB0_741:
	v_lshl_add_u64 v[152:153], s[16:17], 0, v[220:221]
	v_lshl_add_u64 v[154:155], s[14:15], 0, v[220:221]
	s_mov_b64 s[0:1], 0
	s_waitcnt lgkmcnt(0)
	s_nop 0
	v_mfma_f32_16x16x32_bf16 v[148:151], v[4:7], v[20:23], 0
	s_and_b32 s14, s22, 0x10000
	s_xor_b32 s15, s14, 0x10000
	v_add_u32_e32 v168, s14, v222
	v_add_u32_e32 v169, s15, v222
	v_bitop3_b32 v170, s22, v223, v233 bitop3:0xce
	v_or_b32_e32 v171, s14, v223
	ds_read_b128 v[156:159], v168 offset:4096
	ds_read_b128 v[160:163], v168 offset:6144
	v_mfma_f32_16x16x32_bf16 v[144:147], v[0:3], v[20:23], 0
	s_add_i32 s14, s15, s4
	v_lshl_add_u64 v[164:165], v[152:153], 0, s[0:1]
	v_mfma_f32_16x16x32_bf16 v[140:143], v[12:15], v[20:23], 0
	v_lshl_add_u64 v[166:167], v[164:165], 0, s[38:39]
	s_mov_b32 m0, s14
	v_mfma_f32_16x16x32_bf16 v[20:23], v[8:11], v[20:23], 0
	s_add_i32 s15, s14, 0x8000
	global_load_lds_dwordx4 v[166:167], off
	v_mfma_f32_16x16x32_bf16 v[132:135], v[4:7], v[16:19], 0
	v_lshl_add_u64 v[166:167], v[164:165], 0, s[82:83]
	s_add_i32 m0, s14, 0x2000
	v_mfma_f32_16x16x32_bf16 v[128:131], v[0:3], v[16:19], 0
	global_load_lds_dwordx4 v[166:167], off
	v_lshl_add_u64 v[166:167], v[164:165], 0, s[78:79]
	v_mfma_f32_16x16x32_bf16 v[124:127], v[12:15], v[16:19], 0
	s_add_i32 m0, s14, 0x4000
	v_lshl_add_u64 v[164:165], v[164:165], 0, s[2:3]
	v_mfma_f32_16x16x32_bf16 v[16:19], v[8:11], v[16:19], 0
	global_load_lds_dwordx4 v[166:167], off
	s_add_i32 m0, s14, 0x6000
	s_waitcnt lgkmcnt(1)
	v_mfma_f32_16x16x32_bf16 v[116:119], v[4:7], v[156:159], 0
	s_nop 0
	ds_read_b128 v[120:123], v168 offset:8192
	ds_read_b128 v[136:139], v168 offset:10240
	global_load_lds_dwordx4 v[164:165], off
	v_lshl_add_u64 v[164:165], v[154:155], 0, s[0:1]
	v_mfma_f32_16x16x32_bf16 v[112:115], v[0:3], v[156:159], 0
	v_lshl_add_u64 v[166:167], v[164:165], 0, s[38:39]
	s_mov_b32 m0, s15
	v_mfma_f32_16x16x32_bf16 v[108:111], v[12:15], v[156:159], 0
	global_load_lds_dwordx4 v[166:167], off
	v_lshl_add_u64 v[166:167], v[164:165], 0, s[82:83]
	v_mfma_f32_16x16x32_bf16 v[104:107], v[8:11], v[156:159], 0
	s_add_i32 m0, s14, 0xa000
	s_waitcnt lgkmcnt(2)
	v_mfma_f32_16x16x32_bf16 v[100:103], v[4:7], v[160:163], 0
	global_load_lds_dwordx4 v[166:167], off
	v_lshl_add_u64 v[166:167], v[164:165], 0, s[78:79]
	v_mfma_f32_16x16x32_bf16 v[96:99], v[0:3], v[160:163], 0
	s_add_i32 m0, s14, 0xc000
	v_lshl_add_u64 v[164:165], v[164:165], 0, s[2:3]
	v_mfma_f32_16x16x32_bf16 v[92:95], v[12:15], v[160:163], 0
	global_load_lds_dwordx4 v[166:167], off
	s_add_i32 m0, s14, 0xe000
	v_mfma_f32_16x16x32_bf16 v[88:91], v[8:11], v[160:163], 0
	global_load_lds_dwordx4 v[164:165], off
	s_waitcnt lgkmcnt(1)
	v_mfma_f32_16x16x32_bf16 v[84:87], v[4:7], v[120:123], 0
	ds_read_b128 v[156:159], v168 offset:12288
	ds_read_b128 v[160:163], v168 offset:14336
	v_mfma_f32_16x16x32_bf16 v[80:83], v[0:3], v[120:123], 0
	v_mfma_f32_16x16x32_bf16 v[76:79], v[12:15], v[120:123], 0
	v_mfma_f32_16x16x32_bf16 v[72:75], v[8:11], v[120:123], 0
	s_waitcnt lgkmcnt(2)
	v_mfma_f32_16x16x32_bf16 v[68:71], v[4:7], v[136:139], 0
	v_mfma_f32_16x16x32_bf16 v[64:67], v[0:3], v[136:139], 0
	v_mfma_f32_16x16x32_bf16 v[60:63], v[12:15], v[136:139], 0
	v_mfma_f32_16x16x32_bf16 v[56:59], v[8:11], v[136:139], 0
	s_waitcnt lgkmcnt(1)
	v_mfma_f32_16x16x32_bf16 v[52:55], v[4:7], v[156:159], 0
	ds_read_b128 v[120:123], v168 offset:1024
	ds_read_b128 v[164:167], v168 offset:3072
	v_mfma_f32_16x16x32_bf16 v[48:51], v[0:3], v[156:159], 0
	v_mfma_f32_16x16x32_bf16 v[44:47], v[12:15], v[156:159], 0
	v_mfma_f32_16x16x32_bf16 v[40:43], v[8:11], v[156:159], 0
	s_waitcnt lgkmcnt(2)
	v_mfma_f32_16x16x32_bf16 v[4:7], v[4:7], v[160:163], 0
	v_mfma_f32_16x16x32_bf16 v[0:3], v[0:3], v[160:163], 0
	v_mfma_f32_16x16x32_bf16 v[12:15], v[12:15], v[160:163], 0
	v_mfma_f32_16x16x32_bf16 v[8:11], v[8:11], v[160:163], 0
	ds_read_b128 v[24:27], v171 offset:33792
	ds_read_b128 v[28:31], v171 offset:35840
	ds_read_b128 v[156:159], v171 offset:37888
	ds_read_b128 v[160:163], v171 offset:39936
	s_waitcnt lgkmcnt(0)
	v_mfma_f32_16x16x32_bf16 v[148:151], v[24:27], v[120:123], v[148:151]
	ds_read_b128 v[32:35], v168 offset:5120
	ds_read_b128 v[36:39], v168 offset:7168
	v_mfma_f32_16x16x32_bf16 v[144:147], v[28:31], v[120:123], v[144:147]
	v_mfma_f32_16x16x32_bf16 v[140:143], v[156:159], v[120:123], v[140:143]
	v_mfma_f32_16x16x32_bf16 v[136:139], v[160:163], v[120:123], v[20:23]
	v_mfma_f32_16x16x32_bf16 v[132:135], v[24:27], v[164:167], v[132:135]
	v_mfma_f32_16x16x32_bf16 v[128:131], v[28:31], v[164:167], v[128:131]
	v_mfma_f32_16x16x32_bf16 v[124:127], v[156:159], v[164:167], v[124:127]
	v_mfma_f32_16x16x32_bf16 v[120:123], v[160:163], v[164:167], v[16:19]
	s_waitcnt lgkmcnt(1)
	v_mfma_f32_16x16x32_bf16 v[116:119], v[24:27], v[32:35], v[116:119]
	s_nop 0
	ds_read_b128 v[16:19], v168 offset:9216
	ds_read_b128 v[20:23], v168 offset:11264
	v_mfma_f32_16x16x32_bf16 v[112:115], v[28:31], v[32:35], v[112:115]
	v_mfma_f32_16x16x32_bf16 v[108:111], v[156:159], v[32:35], v[108:111]
	v_mfma_f32_16x16x32_bf16 v[104:107], v[160:163], v[32:35], v[104:107]
	s_waitcnt lgkmcnt(2)
	v_mfma_f32_16x16x32_bf16 v[100:103], v[24:27], v[36:39], v[100:103]
	v_mfma_f32_16x16x32_bf16 v[96:99], v[28:31], v[36:39], v[96:99]
	v_mfma_f32_16x16x32_bf16 v[92:95], v[156:159], v[36:39], v[92:95]
	v_mfma_f32_16x16x32_bf16 v[88:91], v[160:163], v[36:39], v[88:91]
	s_waitcnt lgkmcnt(1)
	v_mfma_f32_16x16x32_bf16 v[84:87], v[24:27], v[16:19], v[84:87]
	ds_read_b128 v[32:35], v168 offset:13312
	ds_read_b128 v[164:167], v168 offset:15360
	v_mfma_f32_16x16x32_bf16 v[80:83], v[28:31], v[16:19], v[80:83]
	v_mfma_f32_16x16x32_bf16 v[76:79], v[156:159], v[16:19], v[76:79]
	v_mfma_f32_16x16x32_bf16 v[72:75], v[160:163], v[16:19], v[72:75]
	s_waitcnt lgkmcnt(2)
	v_mfma_f32_16x16x32_bf16 v[68:71], v[24:27], v[20:23], v[68:71]
	v_mfma_f32_16x16x32_bf16 v[64:67], v[28:31], v[20:23], v[64:67]
	v_mfma_f32_16x16x32_bf16 v[60:63], v[156:159], v[20:23], v[60:63]
	v_mfma_f32_16x16x32_bf16 v[56:59], v[160:163], v[20:23], v[56:59]
	s_waitcnt lgkmcnt(1)
	v_mfma_f32_16x16x32_bf16 v[52:55], v[24:27], v[32:35], v[52:55]
	s_waitcnt vmcnt(0)
	s_waitcnt lgkmcnt(0)
	s_barrier
	ds_read_b128 v[20:23], v169
	ds_read_b128 v[16:19], v169 offset:2048
	v_mfma_f32_16x16x32_bf16 v[48:51], v[28:31], v[32:35], v[48:51]
	v_mfma_f32_16x16x32_bf16 v[44:47], v[156:159], v[32:35], v[44:47]
	v_mfma_f32_16x16x32_bf16 v[40:43], v[160:163], v[32:35], v[40:43]
	v_mfma_f32_16x16x32_bf16 v[36:39], v[24:27], v[164:167], v[4:7]
	v_mfma_f32_16x16x32_bf16 v[32:35], v[28:31], v[164:167], v[0:3]
	v_mfma_f32_16x16x32_bf16 v[28:31], v[156:159], v[164:167], v[12:15]
	v_mfma_f32_16x16x32_bf16 v[24:27], v[160:163], v[164:167], v[8:11]
	ds_read_b128 v[4:7], v170 offset:32768
	ds_read_b128 v[0:3], v170 offset:34816
	ds_read_b128 v[12:15], v170 offset:36864
	ds_read_b128 v[8:11], v170 offset:38912
	s_add_u32 s0, s0, 0x80
	s_addc_u32 s1, s1, 0
	s_add_i32 s22, s22, 0x10000

; #define WAIT_V(n) asm volatile("s_waitcnt vmcnt(%0)" ::"n"(n) : "memory")
;     ...
;     f32x4 acc[MT][4];
; #pragma unroll
;     for (int m = 0; m < MT; ++m)
; #pragma unroll
;       for (int n = 0; n < 4; ++n) acc[m][n] = f32x4{0.f, 0.f, 0.f, 0.f};
;     for (int t = 0; t < nt; ++t) {
;       const int cur = t & 1;
;       const char* sa = shm + cur * STAGE_B;
;       const char* sn = shm + (cur ^ 1) * STAGE_B;
;       const bool more = (t + 1 < nt) || (nitem < ntiles);
; #pragma unroll
;       for (int ks = 0; ks < 2; ++ks) {
; #pragma unroll
;         for (int p = 0; p < NP; ++p) {
;           const int q = ks * NP + p;
;           acc[p * 2][0] = __builtin_amdgcn_mfma_f32_16x16x32_bf16(Bq[BDBL ? ks : 0][0], Aq[q & 1][0], acc[p * 2][0], 0, 0, 0);
;           __builtin_amdgcn_sched_barrier(0);
;           if (q == 2 * NP - 1) {
;             WAIT_V(0);
;             __syncthreads();
;             if (more) {
;               if constexpr (BDBL) {
; #pragma unroll
;                 for (int n = 0; n < 4; ++n) Bq[0][n] = *(const bf16x8*)(sn + boff + (n * 2 + 0) * 1024);
;               }
; #pragma unroll
;               for (int i = 0; i < 2; ++i) Aq[0][i] = *(const bf16x8*)(sn + aoff + (i * 2 + 0) * 1024);
;             }
;           } else if (p + 1 < NP) {
; #pragma unroll
;             for (int i = 0; i < 2; ++i) Aq[(q + 1) & 1][i] = *(const bf16x8*)(sa + aoff + (((p + 1) * 2 + i) * 2 + ks) * 1024);
;           } else {
;             if constexpr (BDBL) {
; #pragma unroll
;               for (int n = 0; n < 4; ++n) Bq[1][n] = *(const bf16x8*)(sa + boff + (n * 2 + 1) * 1024);
;             }
; #pragma unroll
;             for (int i = 0; i < 2; ++i) Aq[(q + 1) & 1][i] = *(const bf16x8*)(sa + aoff + (i * 2 + 1) * 1024);
;           }
;           __builtin_amdgcn_sched_barrier(0);
; #pragma unroll
;           for (int i = 0; i < 2; ++i)
; #pragma unroll
;             for (int n = 0; n < 4; ++n)
;               if (i + n > 0)
;                 acc[p * 2 + i][n] = __builtin_amdgcn_mfma_f32_16x16x32_bf16(Bq[BDBL ? ks : 0][n], Aq[q & 1][i], acc[p * 2 + i][n], 0, 0, 0);
;           __builtin_amdgcn_sched_barrier(0);
;           if (q == GLDS_AT) {
;             if (t + 1 < nt) GLDS_STAGE(cur ^ 1, t + 1, Ab, Bb);
;             else if (nitem < ntiles) GLDS_STAGE(0, 0, nAb, nBb);
;             __builtin_amdgcn_sched_barrier(0);
;           }
.LBB0_1057:
	v_lshl_add_u64 v[152:153], s[0:1], 0, v[226:227]
	v_lshl_add_u64 v[154:155], s[18:19], 0, v[226:227]
	s_mov_b64 s[0:1], 0
	s_waitcnt lgkmcnt(0)
	s_nop 0
	v_mfma_f32_16x16x32_bf16 v[148:151], v[12:15], v[20:23], 0
	s_and_b32 s18, s50, 0x10000
	s_xor_b32 s19, s18, 0x10000
	v_add_u32_e32 v184, s18, v240
	v_or_b32_e32 v176, s18, v242
	v_bitop3_b32 v185, s50, v242, v233 bitop3:0xce
	v_add_u32_e32 v186, s19, v240
	ds_read_b128 v[156:159], v184 offset:4096
	ds_read_b128 v[160:163], v184 offset:6144
	v_mfma_f32_16x16x32_bf16 v[144:147], v[8:11], v[20:23], 0
	s_add_i32 s18, s19, s20
	v_lshl_add_u64 v[180:181], v[152:153], 0, s[0:1]
	v_mfma_f32_16x16x32_bf16 v[140:143], v[4:7], v[20:23], 0
	v_lshl_add_u64 v[182:183], v[180:181], 0, s[38:39]
	s_mov_b32 m0, s18
	v_mfma_f32_16x16x32_bf16 v[20:23], v[0:3], v[20:23], 0
	s_add_i32 s19, s18, 0x8000
	global_load_lds_dwordx4 v[182:183], off
	v_mfma_f32_16x16x32_bf16 v[132:135], v[12:15], v[16:19], 0
	v_lshl_add_u64 v[182:183], v[180:181], 0, s[82:83]
	s_add_i32 m0, s18, 0x2000
	v_mfma_f32_16x16x32_bf16 v[128:131], v[8:11], v[16:19], 0
	global_load_lds_dwordx4 v[182:183], off
	v_lshl_add_u64 v[182:183], v[180:181], 0, s[78:79]
	v_mfma_f32_16x16x32_bf16 v[124:127], v[4:7], v[16:19], 0
	s_add_i32 m0, s18, 0x4000
	v_lshl_add_u64 v[180:181], v[180:181], 0, s[2:3]
	v_mfma_f32_16x16x32_bf16 v[16:19], v[0:3], v[16:19], 0
	global_load_lds_dwordx4 v[182:183], off
	s_add_i32 m0, s18, 0x6000
	s_waitcnt lgkmcnt(1)
	v_mfma_f32_16x16x32_bf16 v[116:119], v[12:15], v[156:159], 0
	s_nop 0
	ds_read_b128 v[120:123], v184 offset:8192
	ds_read_b128 v[136:139], v184 offset:10240
	global_load_lds_dwordx4 v[180:181], off
	v_lshl_add_u64 v[180:181], v[154:155], 0, s[0:1]
	v_mfma_f32_16x16x32_bf16 v[112:115], v[8:11], v[156:159], 0
	v_lshl_add_u64 v[182:183], v[180:181], 0, s[38:39]
	s_mov_b32 m0, s19
	v_mfma_f32_16x16x32_bf16 v[108:111], v[4:7], v[156:159], 0
	global_load_lds_dwordx4 v[182:183], off
	v_lshl_add_u64 v[182:183], v[180:181], 0, s[82:83]
	v_mfma_f32_16x16x32_bf16 v[104:107], v[0:3], v[156:159], 0
	s_add_i32 m0, s18, 0xa000
	s_waitcnt lgkmcnt(2)
	v_mfma_f32_16x16x32_bf16 v[100:103], v[12:15], v[160:163], 0
	global_load_lds_dwordx4 v[182:183], off
	v_lshl_add_u64 v[182:183], v[180:181], 0, s[78:79]
	v_mfma_f32_16x16x32_bf16 v[96:99], v[8:11], v[160:163], 0
	s_add_i32 m0, s18, 0xc000
	v_lshl_add_u64 v[180:181], v[180:181], 0, s[2:3]
	v_mfma_f32_16x16x32_bf16 v[92:95], v[4:7], v[160:163], 0
	global_load_lds_dwordx4 v[182:183], off
	s_add_i32 m0, s18, 0xe000
	v_mfma_f32_16x16x32_bf16 v[88:91], v[0:3], v[160:163], 0
	global_load_lds_dwordx4 v[180:181], off
	s_waitcnt lgkmcnt(1)
	v_mfma_f32_16x16x32_bf16 v[84:87], v[12:15], v[120:123], 0
	ds_read_b128 v[156:159], v184 offset:12288
	ds_read_b128 v[160:163], v184 offset:14336
	v_mfma_f32_16x16x32_bf16 v[80:83], v[8:11], v[120:123], 0
	v_mfma_f32_16x16x32_bf16 v[76:79], v[4:7], v[120:123], 0
	v_mfma_f32_16x16x32_bf16 v[72:75], v[0:3], v[120:123], 0
	s_waitcnt lgkmcnt(2)
	v_mfma_f32_16x16x32_bf16 v[68:71], v[12:15], v[136:139], 0
	v_mfma_f32_16x16x32_bf16 v[64:67], v[8:11], v[136:139], 0
	v_mfma_f32_16x16x32_bf16 v[60:63], v[4:7], v[136:139], 0
	v_mfma_f32_16x16x32_bf16 v[56:59], v[0:3], v[136:139], 0
	s_waitcnt lgkmcnt(1)
	v_mfma_f32_16x16x32_bf16 v[52:55], v[12:15], v[156:159], 0
	ds_read_b128 v[164:167], v176 offset:33792
	ds_read_b128 v[168:171], v176 offset:35840
	ds_read_b128 v[172:175], v176 offset:37888
	ds_read_b128 v[176:179], v176 offset:39936
	ds_read_b128 v[120:123], v184 offset:1024
	ds_read_b128 v[180:183], v184 offset:3072
	v_mfma_f32_16x16x32_bf16 v[48:51], v[8:11], v[156:159], 0
	v_mfma_f32_16x16x32_bf16 v[44:47], v[4:7], v[156:159], 0
	v_mfma_f32_16x16x32_bf16 v[40:43], v[0:3], v[156:159], 0
	s_waitcnt lgkmcnt(6)
	v_mfma_f32_16x16x32_bf16 v[36:39], v[12:15], v[160:163], 0
	v_mfma_f32_16x16x32_bf16 v[32:35], v[8:11], v[160:163], 0
	v_mfma_f32_16x16x32_bf16 v[28:31], v[4:7], v[160:163], 0
	v_mfma_f32_16x16x32_bf16 v[24:27], v[0:3], v[160:163], 0
	s_waitcnt lgkmcnt(0)
	v_mfma_f32_16x16x32_bf16 v[148:151], v[164:167], v[120:123], v[148:151]
	ds_read_b128 v[0:3], v184 offset:5120
	ds_read_b128 v[4:7], v184 offset:7168
	v_mfma_f32_16x16x32_bf16 v[144:147], v[168:171], v[120:123], v[144:147]
	v_mfma_f32_16x16x32_bf16 v[140:143], v[172:175], v[120:123], v[140:143]
	v_mfma_f32_16x16x32_bf16 v[136:139], v[176:179], v[120:123], v[20:23]
	v_mfma_f32_16x16x32_bf16 v[132:135], v[164:167], v[180:183], v[132:135]
	v_mfma_f32_16x16x32_bf16 v[128:131], v[168:171], v[180:183], v[128:131]
	v_mfma_f32_16x16x32_bf16 v[124:127], v[172:175], v[180:183], v[124:127]
	v_mfma_f32_16x16x32_bf16 v[120:123], v[176:179], v[180:183], v[16:19]
	s_waitcnt lgkmcnt(1)
	v_mfma_f32_16x16x32_bf16 v[116:119], v[164:167], v[0:3], v[116:119]
	ds_read_b128 v[8:11], v184 offset:9216
	ds_read_b128 v[12:15], v184 offset:11264
	v_mfma_f32_16x16x32_bf16 v[112:115], v[168:171], v[0:3], v[112:115]
	v_mfma_f32_16x16x32_bf16 v[108:111], v[172:175], v[0:3], v[108:111]
	v_mfma_f32_16x16x32_bf16 v[104:107], v[176:179], v[0:3], v[104:107]
	s_waitcnt lgkmcnt(2)
	v_mfma_f32_16x16x32_bf16 v[100:103], v[164:167], v[4:7], v[100:103]
	v_mfma_f32_16x16x32_bf16 v[96:99], v[168:171], v[4:7], v[96:99]
	v_mfma_f32_16x16x32_bf16 v[92:95], v[172:175], v[4:7], v[92:95]
	v_mfma_f32_16x16x32_bf16 v[88:91], v[176:179], v[4:7], v[88:91]
	s_waitcnt lgkmcnt(1)
	v_mfma_f32_16x16x32_bf16 v[84:87], v[164:167], v[8:11], v[84:87]
	ds_read_b128 v[156:159], v184 offset:13312
	ds_read_b128 v[160:163], v184 offset:15360
	v_mfma_f32_16x16x32_bf16 v[80:83], v[168:171], v[8:11], v[80:83]
	v_mfma_f32_16x16x32_bf16 v[76:79], v[172:175], v[8:11], v[76:79]
	v_mfma_f32_16x16x32_bf16 v[72:75], v[176:179], v[8:11], v[72:75]
	s_waitcnt lgkmcnt(2)
	v_mfma_f32_16x16x32_bf16 v[68:71], v[164:167], v[12:15], v[68:71]
	v_mfma_f32_16x16x32_bf16 v[64:67], v[168:171], v[12:15], v[64:67]
	v_mfma_f32_16x16x32_bf16 v[60:63], v[172:175], v[12:15], v[60:63]
	v_mfma_f32_16x16x32_bf16 v[56:59], v[176:179], v[12:15], v[56:59]
	s_waitcnt lgkmcnt(1)
	v_mfma_f32_16x16x32_bf16 v[52:55], v[164:167], v[156:159], v[52:55]
	s_waitcnt vmcnt(0)
	s_waitcnt lgkmcnt(0)
	s_barrier
	ds_read_b128 v[12:15], v185 offset:32768
	ds_read_b128 v[8:11], v185 offset:34816
	ds_read_b128 v[4:7], v185 offset:36864
	ds_read_b128 v[0:3], v185 offset:38912
	ds_read_b128 v[20:23], v186
	ds_read_b128 v[16:19], v186 offset:2048
	v_mfma_f32_16x16x32_bf16 v[48:51], v[168:171], v[156:159], v[48:51]
	v_mfma_f32_16x16x32_bf16 v[44:47], v[172:175], v[156:159], v[44:47]
	v_mfma_f32_16x16x32_bf16 v[40:43], v[176:179], v[156:159], v[40:43]
	v_mfma_f32_16x16x32_bf16 v[36:39], v[164:167], v[160:163], v[36:39]
	v_mfma_f32_16x16x32_bf16 v[32:35], v[168:171], v[160:163], v[32:35]
	v_mfma_f32_16x16x32_bf16 v[28:31], v[172:175], v[160:163], v[28:31]
	v_mfma_f32_16x16x32_bf16 v[24:27], v[176:179], v[160:163], v[24:27]
	s_add_u32 s0, s0, 0x80
	s_addc_u32 s1, s1, 0
	s_add_i32 s50, s50, 0x10000

; __device__ __forceinline__ void ln_phase(float* X, u16* H, const float* g, const float* b, const float* shift,
;                                          const float* scale, int M, float* outp, const float* part = nullptr) {
;     ...
;   for (int row = blockIdx.x * 8 + wid; row < M; row += GRID * 8) {
;     float4 v[4];
;     float* xr = X + (size_t)row * DM;
; #pragma unroll
;     for (int i = 0; i < 4; ++i) v[i] = nx[i];
;     {
;       const int nrow = row + GRID * 8;
;       if (nrow < M) {
; #pragma unroll
;         for (int i = 0; i < 4; ++i) nx[i] = *(const float4*)(X + (size_t)nrow * DM + i * 256 + lane * 4);
;       }
;     }
;     if (part != nullptr && row >= MLAT) {
; #pragma unroll
;       for (int i = 0; i < 4; ++i) {
;         const float4 p4 = *(const float4*)(part + (size_t)(row - MLAT) * DM + i * 256 + lane * 4);
;         v[i].x += p4.x; v[i].y += p4.y; v[i].z += p4.z; v[i].w += p4.w;
;       }
;     }
;     float s = 0.f;
; #pragma unroll
;     for (int i = 0; i < 4; ++i) s += v[i].x + v[i].y + v[i].z + v[i].w;
;     const float mu = wave_sum(s) * (1.0f / 1024.0f);
;     float q = 0.f;
; #pragma unroll
;     for (int i = 0; i < 4; ++i) {
;       v[i].x -= mu; v[i].y -= mu; v[i].z -= mu; v[i].w -= mu;
;       q += v[i].x * v[i].x + v[i].y * v[i].y + v[i].z * v[i].z + v[i].w * v[i].w;
;     }
;     const float rstd = rsqrtf(wave_sum(q) * (1.0f / 1024.0f) + EPS);
.LBB0_1205:
	s_or_b64 exec, exec, s[0:1]
	v_mov_b32_e32 v0, v228
	s_barrier
	v_readlane_b32 s0, v254, 38
	v_ashrrev_i32_e32 v1, 6, v0
	v_readlane_b32 s1, v254, 39
	v_add_u32_e32 v48, s0, v1
	v_cmp_gt_i32_e32 vcc, s60, v48
	s_and_saveexec_b64 s[4:5], vcc
	s_cbranch_execz .LBB0_1212
	v_ashrrev_i32_e32 v49, 31, v48
	v_lshlrev_b64 v[32:33], 12, v[48:49]
	v_lshlrev_b32_e32 v1, 4, v0
	v_lshl_add_u64 v[2:3], s[36:37], 0, v[32:33]
	v_and_b32_e32 v224, 0x3f0, v1
	v_lshl_add_u64 v[2:3], v[2:3], 0, v[224:225]
	global_load_dwordx4 v[28:31], v[2:3], off
	global_load_dwordx4 v[16:19], v[2:3], off offset:1024
	global_load_dwordx4 v[20:23], v[2:3], off offset:2048
	global_load_dwordx4 v[24:27], v[2:3], off offset:3072
	v_readlane_b32 s0, v255, 52
	v_readlane_b32 s1, v255, 53
	s_cmp_lg_u64 s[12:13], 0
	v_and_b32_e32 v0, 63, v0
	v_lshl_add_u64 v[36:37], s[0:1], 0, v[224:225]
	v_readlane_b32 s0, v255, 50
	v_readlane_b32 s1, v255, 51
	s_waitcnt vmcnt(4)
	v_lshlrev_b64 v[44:45], 11, v[48:49]
	s_mov_b64 s[6:7], 0
	v_lshl_add_u64 v[38:39], s[0:1], 0, v[224:225]
	v_readlane_b32 s0, v255, 43
	v_readlane_b32 s1, v255, 44
	s_cselect_b64 s[8:9], -1, 0
	v_lshl_add_u64 v[34:35], s[12:13], 0, v[224:225]
	v_lshl_add_u64 v[40:41], s[0:1], 0, v[224:225]
	v_readlane_b32 s0, v255, 47
	v_readlane_b32 s1, v255, 48
	v_lshl_or_b32 v32, v0, 4, v32
	v_lshl_or_b32 v44, v0, 3, v44
	v_lshl_add_u64 v[42:43], s[0:1], 0, v[224:225]
	s_waitcnt vmcnt(0)
	v_mov_b64_e32 v[0:1], v[28:29]
	v_mov_b64_e32 v[2:3], v[30:31]
	v_mov_b64_e32 v[8:9], v[16:17]
	v_mov_b64_e32 v[10:11], v[18:19]
	v_mov_b64_e32 v[12:13], v[20:21]
	v_mov_b64_e32 v[14:15], v[22:23]
	v_mov_b64_e32 v[4:5], v[24:25]
	v_mov_b64_e32 v[6:7], v[26:27]
	s_branch .LBB0_1208
.LBB0_1207:
	s_or_b64 exec, exec, s[10:11]
	v_add_f32_e32 v51, v29, v28
	v_add_f32_e32 v51, v30, v51
	v_add_f32_e32 v52, v17, v16
	v_add_f32_e32 v51, v31, v51
	v_add_f32_e32 v52, v18, v52
	v_add_f32_e32 v51, 0, v51
	v_add_f32_e32 v52, v19, v52
	v_add_f32_e32 v51, v52, v51
	v_add_f32_e32 v52, v21, v20
	v_add_f32_e32 v52, v22, v52
	v_add_f32_e32 v52, v23, v52
	v_add_f32_e32 v51, v52, v51
	v_add_f32_e32 v52, v25, v24
	v_add_f32_e32 v52, v26, v52
	v_add_f32_e32 v52, v27, v52
	v_add_f32_e32 v51, v52, v51
	v_min_i32_e32 v48, 0x4000, v48
	v_ashrrev_i32_e32 v48, 11, v48
	v_add_f32_dpp v51, v51, v51 row_ror:8 row_mask:0xf bank_mask:0xf bound_ctrl:1
	v_mul_i32_i24_e32 v62, 0x2400, v48
	v_ashrrev_i32_e32 v63, 31, v62
	v_add_f32_dpp v51, v51, v51 row_ror:4 row_mask:0xf bank_mask:0xf bound_ctrl:1
	s_and_b64 s[0:1], exec, s[0:1]
	s_or_b64 s[6:7], s[0:1], s[6:7]
	v_add_f32_dpp v51, v51, v51 row_ror:2 row_mask:0xf bank_mask:0xf bound_ctrl:1
	v_lshl_add_u64 v[32:33], v[32:33], 0, s[68:69]
	s_nop 0
	v_add_f32_dpp v51, v51, v51 row_ror:1 row_mask:0xf bank_mask:0xf bound_ctrl:1
	v_mov_b32_e32 v52, v51
	s_nop 1
	v_permlane16_swap_b32_e32 v51, v52
	v_add_f32_e32 v51, v51, v52
	v_mov_b32_e32 v52, v51
	s_nop 1
	v_permlane32_swap_b32_e32 v51, v52
	v_add_f32_e32 v51, v51, v52
	v_mul_f32_e32 v60, 0x3a800000, v51
	v_pk_add_f32 v[64:65], v[28:29], v[60:61] op_sel_hi:[1,0] neg_lo:[0,1] neg_hi:[0,1]
	v_pk_add_f32 v[72:73], v[16:17], v[60:61] op_sel_hi:[1,0] neg_lo:[0,1] neg_hi:[0,1]
	v_pk_mul_f32 v[66:67], v[64:65], v[64:65]
	v_pk_add_f32 v[68:69], v[30:31], v[60:61] op_sel_hi:[1,0] neg_lo:[0,1] neg_hi:[0,1]
	v_pk_mul_f32 v[16:17], v[72:73], v[72:73]
	v_pk_add_f32 v[74:75], v[18:19], v[60:61] op_sel_hi:[1,0] neg_lo:[0,1] neg_hi:[0,1]
	v_pk_mul_f32 v[70:71], v[68:69], v[68:69]
	v_pk_mul_f32 v[18:19], v[74:75], v[74:75]
	v_add_f32_e32 v16, v16, v17
	v_add_f32_e32 v17, v66, v67
	v_pk_add_f32 v[76:77], v[20:21], v[60:61] op_sel_hi:[1,0] neg_lo:[0,1] neg_hi:[0,1]
	v_add_f32_e32 v16, v18, v16
	v_add_f32_e32 v17, v70, v17
	v_pk_mul_f32 v[20:21], v[76:77], v[76:77]
	v_pk_add_f32 v[78:79], v[22:23], v[60:61] op_sel_hi:[1,0] neg_lo:[0,1] neg_hi:[0,1]
	v_add_f32_e32 v16, v19, v16
	v_add_f32_e32 v17, v71, v17
	v_pk_mul_f32 v[22:23], v[78:79], v[78:79]
	v_add_f32_e32 v16, v17, v16
	v_add_f32_e32 v17, v20, v21
	v_pk_add_f32 v[80:81], v[24:25], v[60:61] op_sel_hi:[1,0] neg_lo:[0,1] neg_hi:[0,1]
	v_add_f32_e32 v17, v22, v17
	v_pk_mul_f32 v[24:25], v[80:81], v[80:81]
	v_pk_add_f32 v[60:61], v[26:27], v[60:61] op_sel_hi:[1,0] neg_lo:[0,1] neg_hi:[0,1]
	v_add_f32_e32 v17, v23, v17
	v_pk_mul_f32 v[26:27], v[60:61], v[60:61]
	v_add_f32_e32 v16, v17, v16
	v_add_f32_e32 v17, v24, v25
	v_add_f32_e32 v17, v26, v17
	v_add_f32_e32 v17, v27, v17
	v_add_f32_e32 v16, v17, v16
	v_lshlrev_b64 v[28:29], 2, v[62:63]
	v_lshl_add_u64 v[30:31], v[40:41], 0, v[28:29]
	v_add_f32_dpp v16, v16, v16 row_ror:8 row_mask:0xf bank_mask:0xf bound_ctrl:1
	v_lshl_add_u64 v[28:29], v[42:43], 0, v[28:29]
	v_lshl_add_u64 v[62:63], s[86:87], 0, v[44:45]
	v_add_f32_dpp v16, v16, v16 row_ror:4 row_mask:0xf bank_mask:0xf bound_ctrl:1
	v_lshl_add_u64 v[44:45], v[44:45], 0, s[42:43]
	s_nop 0
	v_add_f32_dpp v16, v16, v16 row_ror:2 row_mask:0xf bank_mask:0xf bound_ctrl:1
	s_nop 1
	v_add_f32_dpp v16, v16, v16 row_ror:1 row_mask:0xf bank_mask:0xf bound_ctrl:1
	v_mov_b32_e32 v17, v16
	s_nop 1
	v_permlane16_swap_b32_e32 v16, v17
	v_add_f32_e32 v16, v16, v17
	v_mov_b32_e32 v17, v16
	s_nop 1
	v_permlane32_swap_b32_e32 v16, v17
	v_add_f32_e32 v16, v16, v17
	v_fmamk_f32 v16, v16, 0x3a800000, v238
	v_cmp_gt_f32_e32 vcc, s49, v16
	v_mul_f32_e32 v17, 0x4b800000, v16
	s_nop 0
	v_cndmask_b32_e32 v16, v16, v17, vcc
	v_rsq_f32_e32 v16, v16
	s_nop 0
	v_mul_f32_e32 v17, 0x45800000, v16
	v_cndmask_b32_e32 v48, v16, v17, vcc
	v_add_co_u32_e32 v46, vcc, s88, v46
	s_nop 1
	v_addc_co_u32_e32 v47, vcc, 0, v47, vcc
	v_add_co_u32_e32 v52, vcc, s95, v62
	s_nop 1
	v_addc_co_u32_e32 v53, vcc, 0, v63, vcc
	s_waitcnt vmcnt(4)
; __device__ __forceinline__ void ln_phase(float* X, u16* H, const float* g, const float* b, const float* shift,
;                                          const float* scale, int M, float* outp, const float* part = nullptr) {
;     ...
;     {
;       const int nrow = row + GRID * 8;
;       if (nrow < M) {
; #pragma unroll
;         for (int i = 0; i < 4; ++i) nx[i] = *(const float4*)(X + (size_t)nrow * DM + i * 256 + lane * 4);
;       }
;     }
;     ...
;     const int cv = row < MLAT ? (row >> 11) : 8;
; #pragma unroll
;     for (int i = 0; i < 4; ++i) {
;       const int col = i * 256 + lane * 4;
;       const float4 gg = *(const float4*)(g + col), bb = *(const float4*)(b + col);
;       float4 y;
;       y.x = v[i].x * rstd * gg.x + bb.x; y.y = v[i].y * rstd * gg.y + bb.y;
;       y.z = v[i].z * rstd * gg.z + bb.z; y.w = v[i].w * rstd * gg.w + bb.w;
;       if (outp) {
;         *(float4*)(outp + (size_t)row * DM + col) = y;
;       } else {
;         *(float4*)(xr + col) = y;
;         const float4 sh = *(const float4*)(shift + cv * 9216 + col), sc = *(const float4*)(scale + cv * 9216 + col);
;         u32x2 pk;
;         pk.x = pack2(y.x * (1.0f + sc.x) + sh.x, y.y * (1.0f + sc.y) + sh.y);
;         pk.y = pack2(y.z * (1.0f + sc.z) + sh.z, y.w * (1.0f + sc.w) + sh.w);
;         *(u32x2*)(H + (size_t)row * DM + col) = pk;
;       }
;     }
	v_pk_mul_f32 v[16:17], v[64:65], v[48:49] op_sel_hi:[1,0]
	v_pk_mul_f32 v[18:19], v[68:69], v[48:49] op_sel_hi:[1,0]
	v_pk_add_f32 v[100:101], v[100:101], 1.0 op_sel_hi:[1,0]
	v_pk_add_f32 v[102:103], v[102:103], 1.0 op_sel_hi:[1,0]
	v_pk_fma_f32 v[16:17], v[88:89], v[16:17], v[92:93]
	v_pk_fma_f32 v[18:19], v[90:91], v[18:19], v[94:95]
	global_store_dwordx4 v[46:47], v[16:19], off
	v_pk_fma_f32 v[20:21], v[16:17], v[100:101], v[96:97]
	v_pk_fma_f32 v[22:23], v[18:19], v[102:103], v[98:99]
	v_cvt_pk_bf16_f32 v20, v20, v21
	v_cvt_pk_bf16_f32 v21, v22, v23
	global_store_dwordx2 v[52:53], v[20:21], off
	v_pk_mul_f32 v[16:17], v[72:73], v[48:49] op_sel_hi:[1,0]
	v_pk_mul_f32 v[18:19], v[74:75], v[48:49] op_sel_hi:[1,0]
	v_pk_add_f32 v[116:117], v[116:117], 1.0 op_sel_hi:[1,0]
	v_pk_add_f32 v[118:119], v[118:119], 1.0 op_sel_hi:[1,0]
	v_pk_fma_f32 v[16:17], v[104:105], v[16:17], v[108:109]
	v_pk_fma_f32 v[18:19], v[106:107], v[18:19], v[110:111]
	global_store_dwordx4 v[46:47], v[16:19], off offset:1024
	v_pk_fma_f32 v[20:21], v[16:17], v[116:117], v[112:113]
	v_pk_fma_f32 v[22:23], v[18:19], v[118:119], v[114:115]
	v_cvt_pk_bf16_f32 v20, v20, v21
	v_cvt_pk_bf16_f32 v21, v22, v23
	global_store_dwordx2 v[52:53], v[20:21], off offset:512
	v_pk_mul_f32 v[16:17], v[76:77], v[48:49] op_sel_hi:[1,0]
	v_pk_mul_f32 v[18:19], v[78:79], v[48:49] op_sel_hi:[1,0]
	v_pk_add_f32 v[132:133], v[132:133], 1.0 op_sel_hi:[1,0]
	v_pk_add_f32 v[134:135], v[134:135], 1.0 op_sel_hi:[1,0]
	v_pk_fma_f32 v[16:17], v[120:121], v[16:17], v[124:125]
	v_pk_fma_f32 v[18:19], v[122:123], v[18:19], v[126:127]
	global_store_dwordx4 v[46:47], v[16:19], off offset:2048
	v_pk_fma_f32 v[20:21], v[16:17], v[132:133], v[128:129]
	v_pk_fma_f32 v[22:23], v[18:19], v[134:135], v[130:131]
	v_cvt_pk_bf16_f32 v20, v20, v21
	v_cvt_pk_bf16_f32 v21, v22, v23
	global_store_dwordx2 v[52:53], v[20:21], off offset:1024
	v_pk_mul_f32 v[16:17], v[80:81], v[48:49] op_sel_hi:[1,0]
	v_pk_mul_f32 v[18:19], v[60:61], v[48:49] op_sel_hi:[1,0]
	v_pk_add_f32 v[148:149], v[148:149], 1.0 op_sel_hi:[1,0]
	v_pk_add_f32 v[150:151], v[150:151], 1.0 op_sel_hi:[1,0]
	v_pk_fma_f32 v[16:17], v[136:137], v[16:17], v[140:141]
	v_pk_fma_f32 v[18:19], v[138:139], v[18:19], v[142:143]
	global_store_dwordx4 v[46:47], v[16:19], off offset:3072
	v_pk_fma_f32 v[20:21], v[16:17], v[148:149], v[144:145]
	v_pk_fma_f32 v[22:23], v[18:19], v[150:151], v[146:147]
	v_cvt_pk_bf16_f32 v20, v20, v21
	v_cvt_pk_bf16_f32 v21, v22, v23
	global_store_dwordx2 v[52:53], v[20:21], off offset:1536
	v_mov_b32_e32 v48, v49
	s_andn2_b64 exec, exec, s[6:7]
	s_cbranch_execz .LBB0_1212
.LBB0_1208:
	v_add_u32_e32 v49, 0x800, v48
	v_cmp_gt_i32_e32 vcc, s60, v49
	v_cmp_le_i32_e64 s[0:1], s60, v49
	v_lshl_add_u64 v[46:47], s[86:87], 0, v[32:33]
	s_waitcnt vmcnt(11)
	v_mov_b64_e32 v[28:29], v[0:1]
	v_mov_b64_e32 v[30:31], v[2:3]
	s_waitcnt vmcnt(10)
	v_mov_b64_e32 v[16:17], v[8:9]
	v_mov_b64_e32 v[18:19], v[10:11]
	s_waitcnt vmcnt(9)
	v_mov_b64_e32 v[20:21], v[12:13]
	v_mov_b64_e32 v[22:23], v[14:15]
	s_waitcnt vmcnt(8)
	v_mov_b64_e32 v[24:25], v[4:5]
	v_mov_b64_e32 v[26:27], v[6:7]
	v_min_i32_e32 v82, 0x4000, v48
	v_ashrrev_i32_e32 v82, 11, v82
	v_mul_i32_i24_e32 v82, 0x2400, v82
	v_ashrrev_i32_e32 v83, 31, v82
	v_lshlrev_b64 v[82:83], 2, v[82:83]
	v_lshl_add_u64 v[84:85], v[40:41], 0, v[82:83]
	v_lshl_add_u64 v[86:87], v[42:43], 0, v[82:83]
	global_load_dwordx4 v[88:91], v[36:37], off
	global_load_dwordx4 v[92:95], v[38:39], off
	global_load_dwordx4 v[96:99], v[84:85], off
	global_load_dwordx4 v[100:103], v[86:87], off
	global_load_dwordx4 v[104:107], v[36:37], off offset:1024
	global_load_dwordx4 v[108:111], v[38:39], off offset:1024
	global_load_dwordx4 v[112:115], v[84:85], off offset:1024
	global_load_dwordx4 v[116:119], v[86:87], off offset:1024
	global_load_dwordx4 v[120:123], v[36:37], off offset:2048
	global_load_dwordx4 v[124:127], v[38:39], off offset:2048
	global_load_dwordx4 v[128:131], v[84:85], off offset:2048
	global_load_dwordx4 v[132:135], v[86:87], off offset:2048
	global_load_dwordx4 v[136:139], v[36:37], off offset:3072
	global_load_dwordx4 v[140:143], v[38:39], off offset:3072
	global_load_dwordx4 v[144:147], v[84:85], off offset:3072
	global_load_dwordx4 v[148:151], v[86:87], off offset:3072
	s_mov_b64 s[10:11], exec
	v_add_co_u32_e32 v4, vcc, 0xad54000, v46
	s_nop 1
	v_addc_co_u32_e32 v5, vcc, 0, v47, vcc
	global_load_dwordx4 v[0:3], v[4:5], off
	global_load_dwordx4 v[8:11], v[4:5], off offset:1024
	global_load_dwordx4 v[12:15], v[4:5], off offset:2048
	s_nop 0
	global_load_dwordx4 v[4:7], v[4:5], off offset:3072
